# GEMM main loops: LDS fragment reads balanced over the load segments ([12,4,8,0] -> [8,4,8,4] per half-iteration; B0 read one phase earlier behind a counted vmcnt wait)
# speedup vs baseline: 1.0022x; 1.0022x over previous
; #define PG8_STAGE(bufoff, gbase, voff) do { _Pragma("unroll") for (int _i = 0; _i < 2; ++_i) \
;         __builtin_amdgcn_global_load_lds((const unsigned*)((const char*)(gbase) + (voff)[_i]), (LAS unsigned*)(lds + (bufoff) + ldsw + _i * 8192), 16, 0, 0); } while (0)
; #define PG8_LDA(dst, b, h) do { _Pragma("unroll") for (int m = 0; m < 4; ++m) _Pragma("unroll") for (int k = 0; k < 2; ++k) dst[m][k] = *(const LAS bf16x8*)(lds + PG8_SA(b, h) + aoff + m * 2048 + k * 1024); } while (0)
; #define PG8_WAIT_V(n) asm volatile("s_waitcnt vmcnt(" #n ")" ::: "memory")
; #define PG8_BAR __builtin_amdgcn_s_barrier()
; template <class Epi>
; __device__ __forceinline__ void gemm_phase(LAS unsigned char* lds, const Gemm g, const StaticOrder& S, const Epi& E) {
;     ...
;     f32x4 acc[2][2][4][2];
; #pragma unroll
;     for (int a = 0; a < 2; ++a)
; #pragma unroll
;         for (int b = 0; b < 2; ++b)
; #pragma unroll
;             for (int m = 0; m < 4; ++m)
; #pragma unroll
;                 for (int n = 0; n < 2; ++n) acc[a][b][m][n] = (f32x4){0.f, 0.f, 0.f, 0.f};
;     bf16x8 At[4][2], B0[2][2], B1[2][2];
;     const char* cA = (const char*)g.A + (size_t)cur.pm * tstep; const char* cB = (const char*)g.Bt + (size_t)cur.pn * tstep;
;     if (Epi::PRE) E.stash(E.prefetch(cur.pm, tid), lds, 0, tid);
;     PG8_STAGE(PG8_SB(0, 0), cB, voffB); PG8_STAGE(PG8_SA(0, 0), cA, voffA); PG8_STAGE(PG8_SB(0, 1), cB + hstep, voffB); PG8_STAGE(PG8_SA(0, 1), cA + hstep, voffA);
;     if (wr == 1) PG8_BAR;
;     PG8_WAIT_V(4); PG8_BAR;
;     PG8_STAGE(PG8_SB(1, 0), cB + kstep, voffB); PG8_STAGE(PG8_SA(1, 0), cA + kstep, voffA); PG8_STAGE(PG8_SB(1, 1), cB + hstep + kstep, voffB);
;     PG8_WAIT_V(6); PG8_BAR;
;     for (;;) {
;         const bool has_next = S.next(ui + 1, nxt);
;         const char* nA = has_next ? (const char*)g.A + (size_t)nxt.pm * tstep : cA; const char* nB = has_next ? (const char*)g.Bt + (size_t)nxt.pn * tstep : cB;
;         for (int t = 0; t < nt; t += 2) {
;             const bool last = (t == nt - 2);
;             const char* a1 = cA + (size_t)(t + 1) * kstep;
;             const char* a2 = last ? nA : cA + (size_t)(t + 2) * kstep; const char* b2 = last ? nB : cB + (size_t)(t + 2) * kstep;
;             const char* a3 = a2 + kstep; const char* b3 = b2 + kstep;
;             PG8_LDB(B0, 0, 0); PG8_SCHED; PG8_LDA(At, 0, 0); PG8_STAGE(PG8_SA(1, 1), a1 + hstep, voffA);
.LBB0_117:
	v_mov_b32_e32 v127, 0
	s_andn2_b64 vcc, exec, s[6:7]
	v_mov_b32_e32 v126, v127
	v_mov_b32_e32 v125, v127
	v_mov_b32_e32 v124, v127
	v_mov_b32_e32 v123, v127
	v_mov_b32_e32 v122, v127
	v_mov_b32_e32 v121, v127
	v_mov_b32_e32 v120, v127
	v_mov_b32_e32 v111, v127
	v_mov_b32_e32 v110, v127
	v_mov_b32_e32 v109, v127
	v_mov_b32_e32 v108, v127
	v_mov_b32_e32 v107, v127
	v_mov_b32_e32 v106, v127
	v_mov_b32_e32 v105, v127
	v_mov_b32_e32 v104, v127
	v_mov_b32_e32 v95, v127
	v_mov_b32_e32 v94, v127
	v_mov_b32_e32 v93, v127
	v_mov_b32_e32 v92, v127
	v_mov_b32_e32 v91, v127
	v_mov_b32_e32 v90, v127
	v_mov_b32_e32 v89, v127
	v_mov_b32_e32 v88, v127
	v_mov_b32_e32 v79, v127
	v_mov_b32_e32 v78, v127
	v_mov_b32_e32 v77, v127
	v_mov_b32_e32 v76, v127
	v_mov_b32_e32 v75, v127
	v_mov_b32_e32 v74, v127
	v_mov_b32_e32 v73, v127
	v_mov_b32_e32 v72, v127
	v_mov_b32_e32 v119, v127
	v_mov_b32_e32 v118, v127
	v_mov_b32_e32 v117, v127
	v_mov_b32_e32 v116, v127
	v_mov_b32_e32 v115, v127
	v_mov_b32_e32 v114, v127
	v_mov_b32_e32 v113, v127
	v_mov_b32_e32 v112, v127
	v_mov_b32_e32 v103, v127
	v_mov_b32_e32 v102, v127
	v_mov_b32_e32 v101, v127
	v_mov_b32_e32 v100, v127
	v_mov_b32_e32 v99, v127
	v_mov_b32_e32 v98, v127
	v_mov_b32_e32 v97, v127
	v_mov_b32_e32 v96, v127
	v_mov_b32_e32 v87, v127
	v_mov_b32_e32 v86, v127
	v_mov_b32_e32 v85, v127
	v_mov_b32_e32 v84, v127
	v_mov_b32_e32 v83, v127
	v_mov_b32_e32 v82, v127
	v_mov_b32_e32 v81, v127
	v_mov_b32_e32 v80, v127
	v_mov_b32_e32 v71, v127
	v_mov_b32_e32 v70, v127
	v_mov_b32_e32 v69, v127
	v_mov_b32_e32 v68, v127
	v_mov_b32_e32 v67, v127
	v_mov_b32_e32 v66, v127
	v_mov_b32_e32 v65, v127
	v_mov_b32_e32 v64, v127
	v_mov_b32_e32 v63, v127
	v_mov_b32_e32 v62, v127
	v_mov_b32_e32 v61, v127
	v_mov_b32_e32 v60, v127
	v_mov_b32_e32 v59, v127
	v_mov_b32_e32 v58, v127
	v_mov_b32_e32 v57, v127
	v_mov_b32_e32 v56, v127
	v_mov_b32_e32 v47, v127
	v_mov_b32_e32 v46, v127
	v_mov_b32_e32 v45, v127
	v_mov_b32_e32 v44, v127
	v_mov_b32_e32 v43, v127
	v_mov_b32_e32 v42, v127
	v_mov_b32_e32 v41, v127
	v_mov_b32_e32 v40, v127
	v_mov_b32_e32 v31, v127
	v_mov_b32_e32 v30, v127
	v_mov_b32_e32 v29, v127
	v_mov_b32_e32 v28, v127
	v_mov_b32_e32 v27, v127
	v_mov_b32_e32 v26, v127
	v_mov_b32_e32 v25, v127
	v_mov_b32_e32 v24, v127
	v_mov_b32_e32 v15, v127
	v_mov_b32_e32 v14, v127
	v_mov_b32_e32 v13, v127
	v_mov_b32_e32 v12, v127
	v_mov_b32_e32 v11, v127
	v_mov_b32_e32 v10, v127
	v_mov_b32_e32 v9, v127
	v_mov_b32_e32 v8, v127
	v_mov_b32_e32 v55, v127
	v_mov_b32_e32 v54, v127
	v_mov_b32_e32 v53, v127
	v_mov_b32_e32 v52, v127
	v_mov_b32_e32 v51, v127
	v_mov_b32_e32 v50, v127
	v_mov_b32_e32 v49, v127
	v_mov_b32_e32 v48, v127
	v_mov_b32_e32 v39, v127
	v_mov_b32_e32 v38, v127
	v_mov_b32_e32 v37, v127
	v_mov_b32_e32 v36, v127
	v_mov_b32_e32 v35, v127
	v_mov_b32_e32 v34, v127
	v_mov_b32_e32 v33, v127
	v_mov_b32_e32 v32, v127
	v_mov_b32_e32 v23, v127
	v_mov_b32_e32 v22, v127
	v_mov_b32_e32 v21, v127
	v_mov_b32_e32 v20, v127
	v_mov_b32_e32 v19, v127
	v_mov_b32_e32 v18, v127
	v_mov_b32_e32 v17, v127
	v_mov_b32_e32 v16, v127
	v_mov_b32_e32 v7, v127
	v_mov_b32_e32 v6, v127
	v_mov_b32_e32 v5, v127
	v_mov_b32_e32 v4, v127
	v_mov_b32_e32 v3, v127
	v_mov_b32_e32 v2, v127
	s_waitcnt lgkmcnt(0)
	v_mov_b32_e32 v1, v127
	v_mov_b32_e32 v0, v127
	s_cbranch_vccnz .LBB0_120
	s_add_u32 s39, s14, 0x100
	s_addc_u32 s40, s15, 0
	s_add_u32 s14, s16, 0x80
	v_mov_b32_e32 v0, 0
	s_addc_u32 s15, s17, 0
	s_mov_b32 s16, 0
	v_mov_b32_e32 v1, v0
	v_mov_b32_e32 v2, v0
	v_mov_b32_e32 v3, v0
	v_mov_b32_e32 v4, v0
	v_mov_b32_e32 v5, v0
	v_mov_b32_e32 v6, v0
	v_mov_b32_e32 v7, v0
	v_mov_b32_e32 v16, v0
	v_mov_b32_e32 v17, v0
	v_mov_b32_e32 v18, v0
	v_mov_b32_e32 v19, v0
	v_mov_b32_e32 v20, v0
	v_mov_b32_e32 v21, v0
	v_mov_b32_e32 v22, v0
	v_mov_b32_e32 v23, v0
	v_mov_b32_e32 v32, v0
	v_mov_b32_e32 v33, v0
	v_mov_b32_e32 v34, v0
	v_mov_b32_e32 v35, v0
	v_mov_b32_e32 v36, v0
	v_mov_b32_e32 v37, v0
	v_mov_b32_e32 v38, v0
	v_mov_b32_e32 v39, v0
	v_mov_b32_e32 v48, v0
	v_mov_b32_e32 v49, v0
	v_mov_b32_e32 v50, v0
	v_mov_b32_e32 v51, v0
	v_mov_b32_e32 v52, v0
	v_mov_b32_e32 v53, v0
	v_mov_b32_e32 v54, v0
	v_mov_b32_e32 v55, v0
	v_mov_b32_e32 v8, v0
	v_mov_b32_e32 v9, v0
	v_mov_b32_e32 v10, v0
	v_mov_b32_e32 v11, v0
	v_mov_b32_e32 v12, v0
	v_mov_b32_e32 v13, v0
	v_mov_b32_e32 v14, v0
	v_mov_b32_e32 v15, v0
	v_mov_b32_e32 v24, v0
	v_mov_b32_e32 v25, v0
	v_mov_b32_e32 v26, v0
	v_mov_b32_e32 v27, v0
	v_mov_b32_e32 v28, v0
	v_mov_b32_e32 v29, v0
	v_mov_b32_e32 v30, v0
	v_mov_b32_e32 v31, v0
	v_mov_b32_e32 v40, v0
	v_mov_b32_e32 v41, v0
	v_mov_b32_e32 v42, v0
	v_mov_b32_e32 v43, v0
	v_mov_b32_e32 v44, v0
	v_mov_b32_e32 v45, v0
	v_mov_b32_e32 v46, v0
	v_mov_b32_e32 v47, v0
	v_mov_b32_e32 v56, v0
	v_mov_b32_e32 v57, v0
	v_mov_b32_e32 v58, v0
	v_mov_b32_e32 v59, v0
	v_mov_b32_e32 v60, v0
	v_mov_b32_e32 v61, v0
	v_mov_b32_e32 v62, v0
	v_mov_b32_e32 v63, v0
	v_mov_b32_e32 v64, v0
	v_mov_b32_e32 v65, v0
	v_mov_b32_e32 v66, v0
	v_mov_b32_e32 v67, v0
	v_mov_b32_e32 v68, v0
	v_mov_b32_e32 v69, v0
	v_mov_b32_e32 v70, v0
	v_mov_b32_e32 v71, v0
	v_mov_b32_e32 v80, v0
	v_mov_b32_e32 v81, v0
	v_mov_b32_e32 v82, v0
	v_mov_b32_e32 v83, v0
	v_mov_b32_e32 v84, v0
	v_mov_b32_e32 v85, v0
	v_mov_b32_e32 v86, v0
	v_mov_b32_e32 v87, v0
	v_mov_b32_e32 v96, v0
	v_mov_b32_e32 v97, v0
	v_mov_b32_e32 v98, v0
	v_mov_b32_e32 v99, v0
	v_mov_b32_e32 v100, v0
	v_mov_b32_e32 v101, v0
	v_mov_b32_e32 v102, v0
	v_mov_b32_e32 v103, v0
	v_mov_b32_e32 v112, v0
	v_mov_b32_e32 v113, v0
	v_mov_b32_e32 v114, v0
	v_mov_b32_e32 v115, v0
	v_mov_b32_e32 v116, v0
	v_mov_b32_e32 v117, v0
	v_mov_b32_e32 v118, v0
	v_mov_b32_e32 v119, v0
	v_mov_b32_e32 v72, v0
	v_mov_b32_e32 v73, v0
	v_mov_b32_e32 v74, v0
	v_mov_b32_e32 v75, v0
	v_mov_b32_e32 v76, v0
	v_mov_b32_e32 v77, v0
	v_mov_b32_e32 v78, v0
	v_mov_b32_e32 v79, v0
	v_mov_b32_e32 v88, v0
	v_mov_b32_e32 v89, v0
	v_mov_b32_e32 v90, v0
	v_mov_b32_e32 v91, v0
	v_mov_b32_e32 v92, v0
	v_mov_b32_e32 v93, v0
	v_mov_b32_e32 v94, v0
	v_mov_b32_e32 v95, v0
	v_mov_b32_e32 v104, v0
	v_mov_b32_e32 v105, v0
	v_mov_b32_e32 v106, v0
	v_mov_b32_e32 v107, v0
	v_mov_b32_e32 v108, v0
	v_mov_b32_e32 v109, v0
	v_mov_b32_e32 v110, v0
	v_mov_b32_e32 v111, v0
	v_mov_b32_e32 v120, v0
	v_mov_b32_e32 v121, v0
	v_mov_b32_e32 v122, v0
	v_mov_b32_e32 v123, v0
	v_mov_b32_e32 v124, v0
	v_mov_b32_e32 v125, v0
	v_mov_b32_e32 v126, v0
	v_mov_b32_e32 v127, v0
	s_mov_b64 s[44:45], 0x80
	v_add_u32_e32 v224, 0x10000, v245
	v_add_u32_e32 v225, 0x14000, v245
	v_add_u32_e32 v226, 0x18000, v245
	v_add_u32_e32 v227, 0x1c000, v245
	s_add_i32 s86, s23, 0x10000
	s_add_i32 s87, s23, 0x14000
	s_add_i32 s88, s23, 0x18000
	s_add_i32 s89, s23, 0x1c000
	ds_read_b128 v[128:131], v224
	ds_read_b128 v[132:135], v224 offset:1024
	ds_read_b128 v[136:139], v224 offset:2048
	ds_read_b128 v[140:143], v224 offset:3072
; #define PG8_STAGE(bufoff, gbase, voff) do { _Pragma("unroll") for (int _i = 0; _i < 2; ++_i) \
;         __builtin_amdgcn_global_load_lds((const unsigned*)((const char*)(gbase) + (voff)[_i]), (LAS unsigned*)(lds + (bufoff) + ldsw + _i * 8192), 16, 0, 0); } while (0)
; #define PG8_LDA(dst, b, h) do { _Pragma("unroll") for (int m = 0; m < 4; ++m) _Pragma("unroll") for (int k = 0; k < 2; ++k) dst[m][k] = *(const LAS bf16x8*)(lds + PG8_SA(b, h) + aoff + m * 2048 + k * 1024); } while (0)
; #define PG8_LDB(dst, b, h) do { _Pragma("unroll") for (int n = 0; n < 2; ++n) _Pragma("unroll") for (int k = 0; k < 2; ++k) dst[n][k] = *(const LAS bf16x8*)(lds + PG8_SB(b, h) + boff + n * 2048 + k * 1024); } while (0)
; #define PG8_MMA(ai, bj, At, Bt) do { __builtin_amdgcn_s_setprio(1); _Pragma("unroll") for (int m = 0; m < 4; ++m) _Pragma("unroll") for (int n = 0; n < 2; ++n) _Pragma("unroll") for (int k = 0; k < 2; ++k) \
;         acc[ai][bj][m][n] = __builtin_amdgcn_mfma_f32_16x16x32_bf16(Bt[n][k], At[m][k], acc[ai][bj][m][n], 0, 0, 0); __builtin_amdgcn_s_setprio(0); } while (0)
; #define PG8_WAIT_V(n) asm volatile("s_waitcnt vmcnt(" #n ")" ::: "memory")
; #define PG8_WAIT_L(n) asm volatile("s_waitcnt lgkmcnt(" #n ")" ::: "memory")
; template <class Epi>
; __device__ __forceinline__ void gemm_phase(LAS unsigned char* lds, const Gemm g, const StaticOrder& S, const Epi& E) {
;     ...
;         for (int t = 0; t < nt; t += 2) {
;             const bool last = (t == nt - 2);
;             const char* a1 = cA + (size_t)(t + 1) * kstep;
;             const char* a2 = last ? nA : cA + (size_t)(t + 2) * kstep; const char* b2 = last ? nB : cB + (size_t)(t + 2) * kstep;
;             const char* a3 = a2 + kstep; const char* b3 = b2 + kstep;
;             PG8_LDB(B0, 0, 0); PG8_SCHED; PG8_LDA(At, 0, 0); PG8_STAGE(PG8_SA(1, 1), a1 + hstep, voffA);
;             PG8_WAIT_L(8); PG8_BAR; PG8_WAIT_L(0); PG8_MMA(0, 0, At, B0); PG8_BAR; PG8_SCHED;
;             PG8_LDB(B1, 0, 1); PG8_STAGE(PG8_SB(0, 0), b2, voffB);
;             PG8_BAR; PG8_WAIT_L(0); PG8_MMA(0, 1, At, B1); PG8_BAR;
;             PG8_LDA(At, 0, 1); PG8_STAGE(PG8_SA(0, 0), a2, voffA);
;             PG8_BAR; PG8_WAIT_L(0); PG8_MMA(1, 0, At, B0); PG8_BAR; PG8_SCHED;
;             PG8_STAGE(PG8_SB(0, 1), b2 + hstep, voffB);
;             PG8_WAIT_V(6); PG8_BAR; PG8_MMA(1, 1, At, B1); PG8_BAR;
.LBB0_119:
	s_add_i32 s41, s16, 2
	s_add_u32 s18, s14, 0x80
	s_addc_u32 s17, s15, 0
	s_cmp_eq_u32 s31, s16
	s_cselect_b32 s16, s10, s18
	s_cselect_b32 s17, s11, s17
	s_cselect_b32 s19, s13, s40
	s_cselect_b32 s18, s12, s39
	s_add_i32 m0, s24, 0xc000
	ds_read_b128 v[144:147], v247
	ds_read_b128 v[148:151], v247 offset:1024
	ds_read_b128 v[152:155], v247 offset:2048
	ds_read_b128 v[156:159], v247 offset:3072
	ds_read_b128 v[160:163], v247 offset:4096
	ds_read_b128 v[164:167], v247 offset:5120
	ds_read_b128 v[168:171], v247 offset:6144
	global_load_lds_dwordx4 v210, s[14:15]
	s_add_i32 m0, s24, 0xe000
	ds_read_b128 v[172:175], v247 offset:7168
	global_load_lds_dwordx4 v208, s[14:15]
	s_waitcnt lgkmcnt(8)
	s_barrier
	s_waitcnt lgkmcnt(0)
	v_mfma_f32_16x16x32_bf16 v[124:127], v[128:131], v[144:147], v[124:127]
	v_mfma_f32_16x16x32_bf16 v[120:123], v[136:139], v[144:147], v[120:123]
	v_mfma_f32_16x16x32_bf16 v[108:111], v[128:131], v[152:155], v[108:111]
	v_mfma_f32_16x16x32_bf16 v[104:107], v[136:139], v[152:155], v[104:107]
	v_mfma_f32_16x16x32_bf16 v[92:95], v[128:131], v[160:163], v[92:95]
	v_mfma_f32_16x16x32_bf16 v[88:91], v[136:139], v[160:163], v[88:91]
	v_mfma_f32_16x16x32_bf16 v[76:79], v[128:131], v[168:171], v[76:79]
	v_mfma_f32_16x16x32_bf16 v[72:75], v[136:139], v[168:171], v[72:75]
	v_mfma_f32_16x16x32_bf16 v[124:127], v[132:135], v[148:151], v[124:127]
	v_mfma_f32_16x16x32_bf16 v[120:123], v[140:143], v[148:151], v[120:123]
	v_mfma_f32_16x16x32_bf16 v[108:111], v[132:135], v[156:159], v[108:111]
	v_mfma_f32_16x16x32_bf16 v[104:107], v[140:143], v[156:159], v[104:107]
	v_mfma_f32_16x16x32_bf16 v[92:95], v[132:135], v[164:167], v[92:95]
	v_mfma_f32_16x16x32_bf16 v[88:91], v[140:143], v[164:167], v[88:91]
	v_mfma_f32_16x16x32_bf16 v[76:79], v[132:135], v[172:175], v[76:79]
	v_mfma_f32_16x16x32_bf16 v[72:75], v[140:143], v[172:175], v[72:75]
	s_barrier
	s_add_u32 s80, s18, 0x80
	s_addc_u32 s81, s19, 0
	s_mov_b32 m0, s86
	ds_read_b128 v[176:179], v225
	ds_read_b128 v[180:183], v225 offset:1024
	ds_read_b128 v[184:187], v225 offset:2048
	global_load_lds_dwordx4 v194, s[18:19]
	s_add_i32 m0, s86, 0x2000
	ds_read_b128 v[188:191], v225 offset:3072
	global_load_lds_dwordx4 v206, s[18:19]
	s_barrier
	s_waitcnt lgkmcnt(0)
	v_mfma_f32_16x16x32_bf16 v[116:119], v[176:179], v[144:147], v[116:119]
	v_mfma_f32_16x16x32_bf16 v[112:115], v[184:187], v[144:147], v[112:115]
	v_mfma_f32_16x16x32_bf16 v[100:103], v[176:179], v[152:155], v[100:103]
	v_mfma_f32_16x16x32_bf16 v[96:99], v[184:187], v[152:155], v[96:99]
	v_mfma_f32_16x16x32_bf16 v[84:87], v[176:179], v[160:163], v[84:87]
	v_mfma_f32_16x16x32_bf16 v[80:83], v[184:187], v[160:163], v[80:83]
	v_mfma_f32_16x16x32_bf16 v[68:71], v[176:179], v[168:171], v[68:71]
	v_mfma_f32_16x16x32_bf16 v[64:67], v[184:187], v[168:171], v[64:67]
	v_mfma_f32_16x16x32_bf16 v[116:119], v[180:183], v[148:151], v[116:119]
	v_mfma_f32_16x16x32_bf16 v[112:115], v[188:191], v[148:151], v[112:115]
	v_mfma_f32_16x16x32_bf16 v[100:103], v[180:183], v[156:159], v[100:103]
	v_mfma_f32_16x16x32_bf16 v[96:99], v[188:191], v[156:159], v[96:99]
	v_mfma_f32_16x16x32_bf16 v[84:87], v[180:183], v[164:167], v[84:87]
	v_mfma_f32_16x16x32_bf16 v[80:83], v[188:191], v[164:167], v[80:83]
	v_mfma_f32_16x16x32_bf16 v[68:71], v[180:183], v[172:175], v[68:71]
	v_mfma_f32_16x16x32_bf16 v[64:67], v[188:191], v[172:175], v[64:67]
	s_mov_b32 m0, s24
	s_add_u32 s82, s16, 0x80
	s_addc_u32 s83, s17, 0
	s_barrier
	ds_read_b128 v[144:147], v247 offset:16384
	ds_read_b128 v[148:151], v247 offset:17408
	ds_read_b128 v[152:155], v247 offset:18432
	ds_read_b128 v[156:159], v247 offset:19456
	ds_read_b128 v[160:163], v247 offset:20480
	ds_read_b128 v[164:167], v247 offset:21504
	ds_read_b128 v[168:171], v247 offset:22528
	global_load_lds_dwordx4 v202, s[16:17]
	s_mov_b32 m0, s25
	ds_read_b128 v[172:175], v247 offset:23552
	global_load_lds_dwordx4 v204, s[16:17]
	s_waitcnt vmcnt(10)
	s_barrier
	s_waitcnt lgkmcnt(0)
	v_mfma_f32_16x16x32_bf16 v[60:63], v[128:131], v[144:147], v[60:63]
	v_mfma_f32_16x16x32_bf16 v[56:59], v[136:139], v[144:147], v[56:59]
	v_mfma_f32_16x16x32_bf16 v[44:47], v[128:131], v[152:155], v[44:47]
	v_mfma_f32_16x16x32_bf16 v[40:43], v[136:139], v[152:155], v[40:43]
	v_mfma_f32_16x16x32_bf16 v[28:31], v[128:131], v[160:163], v[28:31]
	v_mfma_f32_16x16x32_bf16 v[24:27], v[136:139], v[160:163], v[24:27]
	v_mfma_f32_16x16x32_bf16 v[12:15], v[128:131], v[168:171], v[12:15]
	v_mfma_f32_16x16x32_bf16 v[8:11], v[136:139], v[168:171], v[8:11]
	v_mfma_f32_16x16x32_bf16 v[60:63], v[132:135], v[148:151], v[60:63]
	v_mfma_f32_16x16x32_bf16 v[56:59], v[140:143], v[148:151], v[56:59]
	v_mfma_f32_16x16x32_bf16 v[44:47], v[132:135], v[156:159], v[44:47]
	v_mfma_f32_16x16x32_bf16 v[40:43], v[140:143], v[156:159], v[40:43]
	v_mfma_f32_16x16x32_bf16 v[28:31], v[132:135], v[164:167], v[28:31]
	v_mfma_f32_16x16x32_bf16 v[24:27], v[140:143], v[164:167], v[24:27]
	v_mfma_f32_16x16x32_bf16 v[12:15], v[132:135], v[172:175], v[12:15]
	v_mfma_f32_16x16x32_bf16 v[8:11], v[140:143], v[172:175], v[8:11]
	s_barrier
	ds_read_b128 v[128:131], v226
	ds_read_b128 v[132:135], v226 offset:1024
	ds_read_b128 v[136:139], v226 offset:2048
	ds_read_b128 v[140:143], v226 offset:3072
	s_add_u32 s18, s18, s0
	s_addc_u32 s19, s19, s1
	s_add_u32 s84, s18, 0x80
	s_mov_b32 m0, s87
	s_addc_u32 s85, s19, 0
	global_load_lds_dwordx4 v194, s[18:19]
	s_add_i32 m0, s87, 0x2000
	s_nop 0
	global_load_lds_dwordx4 v206, s[18:19]
	s_waitcnt vmcnt(6)
	s_barrier
; #define PG8_STAGE(bufoff, gbase, voff) do { _Pragma("unroll") for (int _i = 0; _i < 2; ++_i) \
;         __builtin_amdgcn_global_load_lds((const unsigned*)((const char*)(gbase) + (voff)[_i]), (LAS unsigned*)(lds + (bufoff) + ldsw + _i * 8192), 16, 0, 0); } while (0)
; #define PG8_LDA(dst, b, h) do { _Pragma("unroll") for (int m = 0; m < 4; ++m) _Pragma("unroll") for (int k = 0; k < 2; ++k) dst[m][k] = *(const LAS bf16x8*)(lds + PG8_SA(b, h) + aoff + m * 2048 + k * 1024); } while (0)
; #define PG8_LDB(dst, b, h) do { _Pragma("unroll") for (int n = 0; n < 2; ++n) _Pragma("unroll") for (int k = 0; k < 2; ++k) dst[n][k] = *(const LAS bf16x8*)(lds + PG8_SB(b, h) + boff + n * 2048 + k * 1024); } while (0)
; #define PG8_MMA(ai, bj, At, Bt) do { __builtin_amdgcn_s_setprio(1); _Pragma("unroll") for (int m = 0; m < 4; ++m) _Pragma("unroll") for (int n = 0; n < 2; ++n) _Pragma("unroll") for (int k = 0; k < 2; ++k) \
;         acc[ai][bj][m][n] = __builtin_amdgcn_mfma_f32_16x16x32_bf16(Bt[n][k], At[m][k], acc[ai][bj][m][n], 0, 0, 0); __builtin_amdgcn_s_setprio(0); } while (0)
; #define PG8_WAIT_V(n) asm volatile("s_waitcnt vmcnt(" #n ")" ::: "memory")
; #define PG8_WAIT_L(n) asm volatile("s_waitcnt lgkmcnt(" #n ")" ::: "memory")
; #define PG8_BAR __builtin_amdgcn_s_barrier()
; #define PG8_SCHED __builtin_amdgcn_sched_barrier(0)
; template <class Epi>
; __device__ __forceinline__ void gemm_phase(LAS unsigned char* lds, const Gemm g, const StaticOrder& S, const Epi& E) {
;     ...
;             PG8_WAIT_V(6); PG8_BAR; PG8_MMA(1, 1, At, B1); PG8_BAR;
;             PG8_LDB(B0, 1, 0); PG8_SCHED; PG8_LDA(At, 1, 0); PG8_STAGE(PG8_SA(0, 1), a2 + hstep, voffA);
;             PG8_WAIT_L(8); PG8_BAR; PG8_WAIT_L(0); PG8_MMA(0, 0, At, B0); PG8_BAR; PG8_SCHED;
;             PG8_LDB(B1, 1, 1); PG8_STAGE(PG8_SB(1, 0), b3, voffB);
;             PG8_BAR; PG8_WAIT_L(0); PG8_MMA(0, 1, At, B1); PG8_BAR;
	v_mfma_f32_16x16x32_bf16 v[52:55], v[176:179], v[144:147], v[52:55]
	v_mfma_f32_16x16x32_bf16 v[48:51], v[184:187], v[144:147], v[48:51]
	v_mfma_f32_16x16x32_bf16 v[36:39], v[176:179], v[152:155], v[36:39]
	v_mfma_f32_16x16x32_bf16 v[32:35], v[184:187], v[152:155], v[32:35]
	v_mfma_f32_16x16x32_bf16 v[20:23], v[176:179], v[160:163], v[20:23]
	v_mfma_f32_16x16x32_bf16 v[16:19], v[184:187], v[160:163], v[16:19]
	v_mfma_f32_16x16x32_bf16 v[4:7], v[176:179], v[168:171], v[4:7]
	v_mfma_f32_16x16x32_bf16 v[0:3], v[184:187], v[168:171], v[0:3]
	v_mfma_f32_16x16x32_bf16 v[52:55], v[180:183], v[148:151], v[52:55]
	v_mfma_f32_16x16x32_bf16 v[48:51], v[188:191], v[148:151], v[48:51]
	v_mfma_f32_16x16x32_bf16 v[36:39], v[180:183], v[156:159], v[36:39]
	v_mfma_f32_16x16x32_bf16 v[32:35], v[188:191], v[156:159], v[32:35]
	v_mfma_f32_16x16x32_bf16 v[20:23], v[180:183], v[164:167], v[20:23]
	v_mfma_f32_16x16x32_bf16 v[16:19], v[188:191], v[164:167], v[16:19]
	v_mfma_f32_16x16x32_bf16 v[4:7], v[180:183], v[172:175], v[4:7]
	v_mfma_f32_16x16x32_bf16 v[0:3], v[188:191], v[172:175], v[0:3]
	s_barrier
	s_add_u32 s16, s16, s0
	s_addc_u32 s17, s17, s1
	s_mov_b32 m0, s26
	ds_read_b128 v[144:147], v247 offset:32768
	ds_read_b128 v[148:151], v247 offset:33792
	ds_read_b128 v[152:155], v247 offset:34816
	ds_read_b128 v[156:159], v247 offset:35840
	ds_read_b128 v[160:163], v247 offset:36864
	ds_read_b128 v[164:167], v247 offset:37888
	ds_read_b128 v[168:171], v247 offset:38912
	global_load_lds_dwordx4 v202, s[16:17]
	s_mov_b32 m0, s27
	ds_read_b128 v[172:175], v247 offset:39936
	global_load_lds_dwordx4 v204, s[16:17]
	s_waitcnt lgkmcnt(8)
	s_barrier
	s_waitcnt lgkmcnt(0)
	v_mfma_f32_16x16x32_bf16 v[124:127], v[128:131], v[144:147], v[124:127]
	v_mfma_f32_16x16x32_bf16 v[120:123], v[136:139], v[144:147], v[120:123]
	v_mfma_f32_16x16x32_bf16 v[108:111], v[128:131], v[152:155], v[108:111]
	v_mfma_f32_16x16x32_bf16 v[104:107], v[136:139], v[152:155], v[104:107]
	v_mfma_f32_16x16x32_bf16 v[92:95], v[128:131], v[160:163], v[92:95]
	v_mfma_f32_16x16x32_bf16 v[88:91], v[136:139], v[160:163], v[88:91]
	v_mfma_f32_16x16x32_bf16 v[76:79], v[128:131], v[168:171], v[76:79]
	v_mfma_f32_16x16x32_bf16 v[72:75], v[136:139], v[168:171], v[72:75]
	v_mfma_f32_16x16x32_bf16 v[124:127], v[132:135], v[148:151], v[124:127]
	v_mfma_f32_16x16x32_bf16 v[120:123], v[140:143], v[148:151], v[120:123]
	v_mfma_f32_16x16x32_bf16 v[108:111], v[132:135], v[156:159], v[108:111]
	v_mfma_f32_16x16x32_bf16 v[104:107], v[140:143], v[156:159], v[104:107]
	v_mfma_f32_16x16x32_bf16 v[92:95], v[132:135], v[164:167], v[92:95]
	v_mfma_f32_16x16x32_bf16 v[88:91], v[140:143], v[164:167], v[88:91]
	v_mfma_f32_16x16x32_bf16 v[76:79], v[132:135], v[172:175], v[76:79]
	v_mfma_f32_16x16x32_bf16 v[72:75], v[140:143], v[172:175], v[72:75]
	s_barrier
	s_mov_b32 m0, s88
	ds_read_b128 v[176:179], v227
	ds_read_b128 v[180:183], v227 offset:1024
	ds_read_b128 v[184:187], v227 offset:2048
	global_load_lds_dwordx4 v194, s[80:81]
	s_add_i32 m0, s88, 0x2000
	ds_read_b128 v[188:191], v227 offset:3072
	global_load_lds_dwordx4 v206, s[80:81]
	s_barrier
	s_waitcnt lgkmcnt(0)
	v_mfma_f32_16x16x32_bf16 v[116:119], v[176:179], v[144:147], v[116:119]
	v_mfma_f32_16x16x32_bf16 v[112:115], v[184:187], v[144:147], v[112:115]
	v_mfma_f32_16x16x32_bf16 v[100:103], v[176:179], v[152:155], v[100:103]
	v_mfma_f32_16x16x32_bf16 v[96:99], v[184:187], v[152:155], v[96:99]
	v_mfma_f32_16x16x32_bf16 v[84:87], v[176:179], v[160:163], v[84:87]
	v_mfma_f32_16x16x32_bf16 v[80:83], v[184:187], v[160:163], v[80:83]
	v_mfma_f32_16x16x32_bf16 v[68:71], v[176:179], v[168:171], v[68:71]
	v_mfma_f32_16x16x32_bf16 v[64:67], v[184:187], v[168:171], v[64:67]
	v_mfma_f32_16x16x32_bf16 v[116:119], v[180:183], v[148:151], v[116:119]
	v_mfma_f32_16x16x32_bf16 v[112:115], v[188:191], v[148:151], v[112:115]
	v_mfma_f32_16x16x32_bf16 v[100:103], v[180:183], v[156:159], v[100:103]
	v_mfma_f32_16x16x32_bf16 v[96:99], v[188:191], v[156:159], v[96:99]
	v_mfma_f32_16x16x32_bf16 v[84:87], v[180:183], v[164:167], v[84:87]
	v_mfma_f32_16x16x32_bf16 v[80:83], v[188:191], v[164:167], v[80:83]
	v_mfma_f32_16x16x32_bf16 v[68:71], v[180:183], v[172:175], v[68:71]
	v_mfma_f32_16x16x32_bf16 v[64:67], v[188:191], v[172:175], v[64:67]
	s_mov_b32 m0, s28
	s_barrier
; #define PG8_STAGE(bufoff, gbase, voff) do { _Pragma("unroll") for (int _i = 0; _i < 2; ++_i) \
;         __builtin_amdgcn_global_load_lds((const unsigned*)((const char*)(gbase) + (voff)[_i]), (LAS unsigned*)(lds + (bufoff) + ldsw + _i * 8192), 16, 0, 0); } while (0)
; #define PG8_LDA(dst, b, h) do { _Pragma("unroll") for (int m = 0; m < 4; ++m) _Pragma("unroll") for (int k = 0; k < 2; ++k) dst[m][k] = *(const LAS bf16x8*)(lds + PG8_SA(b, h) + aoff + m * 2048 + k * 1024); } while (0)
; #define PG8_MMA(ai, bj, At, Bt) do { __builtin_amdgcn_s_setprio(1); _Pragma("unroll") for (int m = 0; m < 4; ++m) _Pragma("unroll") for (int n = 0; n < 2; ++n) _Pragma("unroll") for (int k = 0; k < 2; ++k) \
;         acc[ai][bj][m][n] = __builtin_amdgcn_mfma_f32_16x16x32_bf16(Bt[n][k], At[m][k], acc[ai][bj][m][n], 0, 0, 0); __builtin_amdgcn_s_setprio(0); } while (0)
; #define PG8_WAIT_V(n) asm volatile("s_waitcnt vmcnt(" #n ")" ::: "memory")
; #define PG8_WAIT_L(n) asm volatile("s_waitcnt lgkmcnt(" #n ")" ::: "memory")
; #define PG8_BAR __builtin_amdgcn_s_barrier()
; #define PG8_SCHED __builtin_amdgcn_sched_barrier(0)
; template <class Epi>
; __device__ __forceinline__ void gemm_phase(LAS unsigned char* lds, const Gemm g, const StaticOrder& S, const Epi& E) {
;     ...
;             PG8_BAR; PG8_WAIT_L(0); PG8_MMA(0, 1, At, B1); PG8_BAR;
;             PG8_LDA(At, 1, 1); PG8_STAGE(PG8_SA(1, 0), a3, voffA);
;             PG8_BAR; PG8_WAIT_L(0); PG8_MMA(1, 0, At, B0); PG8_BAR; PG8_SCHED;
;             PG8_STAGE(PG8_SB(1, 1), b3 + hstep, voffB);
;             PG8_WAIT_V(6); PG8_BAR; PG8_MMA(1, 1, At, B1); PG8_BAR;
;         }
	ds_read_b128 v[144:147], v247 offset:49152
	ds_read_b128 v[148:151], v247 offset:50176
	ds_read_b128 v[152:155], v247 offset:51200
	ds_read_b128 v[156:159], v247 offset:52224
	ds_read_b128 v[160:163], v247 offset:53248
	ds_read_b128 v[164:167], v247 offset:54272
	ds_read_b128 v[168:171], v247 offset:55296
	global_load_lds_dwordx4 v202, s[82:83]
	s_mov_b32 m0, s29
	ds_read_b128 v[172:175], v247 offset:56320
	global_load_lds_dwordx4 v204, s[82:83]
	s_waitcnt vmcnt(10)
	s_barrier
	s_waitcnt lgkmcnt(0)
	v_mfma_f32_16x16x32_bf16 v[60:63], v[128:131], v[144:147], v[60:63]
	v_mfma_f32_16x16x32_bf16 v[56:59], v[136:139], v[144:147], v[56:59]
	v_mfma_f32_16x16x32_bf16 v[44:47], v[128:131], v[152:155], v[44:47]
	v_mfma_f32_16x16x32_bf16 v[40:43], v[136:139], v[152:155], v[40:43]
	v_mfma_f32_16x16x32_bf16 v[28:31], v[128:131], v[160:163], v[28:31]
	v_mfma_f32_16x16x32_bf16 v[24:27], v[136:139], v[160:163], v[24:27]
	v_mfma_f32_16x16x32_bf16 v[12:15], v[128:131], v[168:171], v[12:15]
	v_mfma_f32_16x16x32_bf16 v[8:11], v[136:139], v[168:171], v[8:11]
	v_mfma_f32_16x16x32_bf16 v[60:63], v[132:135], v[148:151], v[60:63]
	v_mfma_f32_16x16x32_bf16 v[56:59], v[140:143], v[148:151], v[56:59]
	v_mfma_f32_16x16x32_bf16 v[44:47], v[132:135], v[156:159], v[44:47]
	v_mfma_f32_16x16x32_bf16 v[40:43], v[140:143], v[156:159], v[40:43]
	v_mfma_f32_16x16x32_bf16 v[28:31], v[132:135], v[164:167], v[28:31]
	v_mfma_f32_16x16x32_bf16 v[24:27], v[140:143], v[164:167], v[24:27]
	v_mfma_f32_16x16x32_bf16 v[12:15], v[132:135], v[172:175], v[12:15]
	v_mfma_f32_16x16x32_bf16 v[8:11], v[140:143], v[172:175], v[8:11]
	s_barrier
	ds_read_b128 v[128:131], v224
	ds_read_b128 v[132:135], v224 offset:1024
	ds_read_b128 v[136:139], v224 offset:2048
	ds_read_b128 v[140:143], v224 offset:3072
	s_mov_b32 m0, s89
	s_nop 0
	global_load_lds_dwordx4 v194, s[84:85]
	s_add_i32 m0, s89, 0x2000
	s_nop 0
	global_load_lds_dwordx4 v206, s[84:85]
	s_waitcnt vmcnt(6)
	s_barrier
	v_mfma_f32_16x16x32_bf16 v[52:55], v[176:179], v[144:147], v[52:55]
	v_mfma_f32_16x16x32_bf16 v[48:51], v[184:187], v[144:147], v[48:51]
	v_mfma_f32_16x16x32_bf16 v[36:39], v[176:179], v[152:155], v[36:39]
	v_mfma_f32_16x16x32_bf16 v[32:35], v[184:187], v[152:155], v[32:35]
	v_mfma_f32_16x16x32_bf16 v[20:23], v[176:179], v[160:163], v[20:23]
	v_mfma_f32_16x16x32_bf16 v[16:19], v[184:187], v[160:163], v[16:19]
	v_mfma_f32_16x16x32_bf16 v[4:7], v[176:179], v[168:171], v[4:7]
	v_mfma_f32_16x16x32_bf16 v[0:3], v[184:187], v[168:171], v[0:3]
	v_mfma_f32_16x16x32_bf16 v[52:55], v[180:183], v[148:151], v[52:55]
	v_mfma_f32_16x16x32_bf16 v[48:51], v[188:191], v[148:151], v[48:51]
	v_mfma_f32_16x16x32_bf16 v[36:39], v[180:183], v[156:159], v[36:39]
	v_mfma_f32_16x16x32_bf16 v[32:35], v[188:191], v[156:159], v[32:35]
	v_mfma_f32_16x16x32_bf16 v[20:23], v[180:183], v[164:167], v[20:23]
	v_mfma_f32_16x16x32_bf16 v[16:19], v[188:191], v[164:167], v[16:19]
	v_mfma_f32_16x16x32_bf16 v[4:7], v[180:183], v[172:175], v[4:7]
	v_mfma_f32_16x16x32_bf16 v[0:3], v[188:191], v[172:175], v[0:3]
	s_add_u32 s39, s39, 0x100
	s_addc_u32 s40, s40, 0
	s_add_u32 s14, s14, 0x100
	s_addc_u32 s15, s15, 0
	s_cmp_ge_i32 s41, s30
	s_mov_b32 s16, s41
	s_barrier
	s_cbranch_scc0 .LBB0_119
	s_waitcnt lgkmcnt(0)

; #define PG8_STAGE(bufoff, gbase, voff) do { _Pragma("unroll") for (int _i = 0; _i < 2; ++_i) \
;         __builtin_amdgcn_global_load_lds((const unsigned*)((const char*)(gbase) + (voff)[_i]), (LAS unsigned*)(lds + (bufoff) + ldsw + _i * 8192), 16, 0, 0); } while (0)
; #define PG8_LDA(dst, b, h) do { _Pragma("unroll") for (int m = 0; m < 4; ++m) _Pragma("unroll") for (int k = 0; k < 2; ++k) dst[m][k] = *(const LAS bf16x8*)(lds + PG8_SA(b, h) + aoff + m * 2048 + k * 1024); } while (0)
; #define PG8_WAIT_V(n) asm volatile("s_waitcnt vmcnt(" #n ")" ::: "memory")
; #define PG8_BAR __builtin_amdgcn_s_barrier()
; template <class Epi>
; __device__ __forceinline__ void gemm_phase(LAS unsigned char* lds, const Gemm g, const StaticOrder& S, const Epi& E) {
;     ...
;     f32x4 acc[2][2][4][2];
; #pragma unroll
;     for (int a = 0; a < 2; ++a)
; #pragma unroll
;         for (int b = 0; b < 2; ++b)
; #pragma unroll
;             for (int m = 0; m < 4; ++m)
; #pragma unroll
;                 for (int n = 0; n < 2; ++n) acc[a][b][m][n] = (f32x4){0.f, 0.f, 0.f, 0.f};
;     bf16x8 At[4][2], B0[2][2], B1[2][2];
;     const char* cA = (const char*)g.A + (size_t)cur.pm * tstep; const char* cB = (const char*)g.Bt + (size_t)cur.pn * tstep;
;     if (Epi::PRE) E.stash(E.prefetch(cur.pm, tid), lds, 0, tid);
;     PG8_STAGE(PG8_SB(0, 0), cB, voffB); PG8_STAGE(PG8_SA(0, 0), cA, voffA); PG8_STAGE(PG8_SB(0, 1), cB + hstep, voffB); PG8_STAGE(PG8_SA(0, 1), cA + hstep, voffA);
;     if (wr == 1) PG8_BAR;
;     PG8_WAIT_V(4); PG8_BAR;
;     PG8_STAGE(PG8_SB(1, 0), cB + kstep, voffB); PG8_STAGE(PG8_SA(1, 0), cA + kstep, voffA); PG8_STAGE(PG8_SB(1, 1), cB + hstep + kstep, voffB);
;     PG8_WAIT_V(6); PG8_BAR;
;     for (;;) {
;         const bool has_next = S.next(ui + 1, nxt);
;         const char* nA = has_next ? (const char*)g.A + (size_t)nxt.pm * tstep : cA; const char* nB = has_next ? (const char*)g.Bt + (size_t)nxt.pn * tstep : cB;
;         for (int t = 0; t < nt; t += 2) {
;             const bool last = (t == nt - 2);
;             const char* a1 = cA + (size_t)(t + 1) * kstep;
;             const char* a2 = last ? nA : cA + (size_t)(t + 2) * kstep; const char* b2 = last ? nB : cB + (size_t)(t + 2) * kstep;
;             const char* a3 = a2 + kstep; const char* b3 = b2 + kstep;
;             PG8_LDB(B0, 0, 0); PG8_SCHED; PG8_LDA(At, 0, 0); PG8_STAGE(PG8_SA(1, 1), a1 + hstep, voffA);
.LBB0_163:
	v_mov_b32_e32 v127, 0
	s_andn2_b64 vcc, exec, s[6:7]
	v_mov_b32_e32 v126, v127
	v_mov_b32_e32 v125, v127
	v_mov_b32_e32 v124, v127
	v_mov_b32_e32 v123, v127
	v_mov_b32_e32 v122, v127
	v_mov_b32_e32 v121, v127
	v_mov_b32_e32 v120, v127
	v_mov_b32_e32 v111, v127
	v_mov_b32_e32 v110, v127
	v_mov_b32_e32 v109, v127
	v_mov_b32_e32 v108, v127
	v_mov_b32_e32 v107, v127
	v_mov_b32_e32 v106, v127
	v_mov_b32_e32 v105, v127
	v_mov_b32_e32 v104, v127
	v_mov_b32_e32 v95, v127
	v_mov_b32_e32 v94, v127
	v_mov_b32_e32 v93, v127
	v_mov_b32_e32 v92, v127
	v_mov_b32_e32 v91, v127
	v_mov_b32_e32 v90, v127
	v_mov_b32_e32 v89, v127
	v_mov_b32_e32 v88, v127
	v_mov_b32_e32 v79, v127
	v_mov_b32_e32 v78, v127
	v_mov_b32_e32 v77, v127
	v_mov_b32_e32 v76, v127
	v_mov_b32_e32 v75, v127
	v_mov_b32_e32 v74, v127
	v_mov_b32_e32 v73, v127
	v_mov_b32_e32 v72, v127
	v_mov_b32_e32 v119, v127
	v_mov_b32_e32 v118, v127
	v_mov_b32_e32 v117, v127
	v_mov_b32_e32 v116, v127
	v_mov_b32_e32 v115, v127
	v_mov_b32_e32 v114, v127
	v_mov_b32_e32 v113, v127
	v_mov_b32_e32 v112, v127
	v_mov_b32_e32 v103, v127
	v_mov_b32_e32 v102, v127
	v_mov_b32_e32 v101, v127
	v_mov_b32_e32 v100, v127
	v_mov_b32_e32 v99, v127
	v_mov_b32_e32 v98, v127
	v_mov_b32_e32 v97, v127
	v_mov_b32_e32 v96, v127
	v_mov_b32_e32 v87, v127
	v_mov_b32_e32 v86, v127
	v_mov_b32_e32 v85, v127
	v_mov_b32_e32 v84, v127
	v_mov_b32_e32 v83, v127
	v_mov_b32_e32 v82, v127
	v_mov_b32_e32 v81, v127
	v_mov_b32_e32 v80, v127
	v_mov_b32_e32 v71, v127
	v_mov_b32_e32 v70, v127
	v_mov_b32_e32 v69, v127
	v_mov_b32_e32 v68, v127
	v_mov_b32_e32 v67, v127
	v_mov_b32_e32 v66, v127
	v_mov_b32_e32 v65, v127
	v_mov_b32_e32 v64, v127
	v_mov_b32_e32 v63, v127
	v_mov_b32_e32 v62, v127
	v_mov_b32_e32 v61, v127
	v_mov_b32_e32 v60, v127
	v_mov_b32_e32 v59, v127
	v_mov_b32_e32 v58, v127
	v_mov_b32_e32 v57, v127
	v_mov_b32_e32 v56, v127
	v_mov_b32_e32 v47, v127
	v_mov_b32_e32 v46, v127
	v_mov_b32_e32 v45, v127
	v_mov_b32_e32 v44, v127
	v_mov_b32_e32 v43, v127
	v_mov_b32_e32 v42, v127
	v_mov_b32_e32 v41, v127
	v_mov_b32_e32 v40, v127
	v_mov_b32_e32 v31, v127
	v_mov_b32_e32 v30, v127
	v_mov_b32_e32 v29, v127
	v_mov_b32_e32 v28, v127
	v_mov_b32_e32 v27, v127
	v_mov_b32_e32 v26, v127
	v_mov_b32_e32 v25, v127
	v_mov_b32_e32 v24, v127
	v_mov_b32_e32 v15, v127
	v_mov_b32_e32 v14, v127
	v_mov_b32_e32 v13, v127
	v_mov_b32_e32 v12, v127
	v_mov_b32_e32 v11, v127
	v_mov_b32_e32 v10, v127
	v_mov_b32_e32 v9, v127
	v_mov_b32_e32 v8, v127
	v_mov_b32_e32 v55, v127
	v_mov_b32_e32 v54, v127
	v_mov_b32_e32 v53, v127
	v_mov_b32_e32 v52, v127
	v_mov_b32_e32 v51, v127
	v_mov_b32_e32 v50, v127
	v_mov_b32_e32 v49, v127
	v_mov_b32_e32 v48, v127
	v_mov_b32_e32 v39, v127
	v_mov_b32_e32 v38, v127
	v_mov_b32_e32 v37, v127
	v_mov_b32_e32 v36, v127
	v_mov_b32_e32 v35, v127
	v_mov_b32_e32 v34, v127
	v_mov_b32_e32 v33, v127
	v_mov_b32_e32 v32, v127
	v_mov_b32_e32 v23, v127
	v_mov_b32_e32 v22, v127
	v_mov_b32_e32 v21, v127
	v_mov_b32_e32 v20, v127
	v_mov_b32_e32 v19, v127
	v_mov_b32_e32 v18, v127
	v_mov_b32_e32 v17, v127
	v_mov_b32_e32 v16, v127
	v_mov_b32_e32 v7, v127
	v_mov_b32_e32 v6, v127
	v_mov_b32_e32 v5, v127
	v_mov_b32_e32 v4, v127
	v_mov_b32_e32 v3, v127
	v_mov_b32_e32 v2, v127
	v_mov_b32_e32 v1, v127
	v_mov_b32_e32 v0, v127
	s_cbranch_vccnz .LBB0_166
	s_add_u32 s42, s18, 0x100
	s_addc_u32 s43, s19, 0
	s_add_u32 s16, s16, 0x80
	v_mov_b32_e32 v0, 0
	s_addc_u32 s17, s17, 0
	s_mov_b32 s18, 0
	v_mov_b32_e32 v1, v0
	v_mov_b32_e32 v2, v0
	v_mov_b32_e32 v3, v0
	v_mov_b32_e32 v4, v0
	v_mov_b32_e32 v5, v0
	v_mov_b32_e32 v6, v0
	v_mov_b32_e32 v7, v0
	v_mov_b32_e32 v16, v0
	v_mov_b32_e32 v17, v0
	v_mov_b32_e32 v18, v0
	v_mov_b32_e32 v19, v0
	v_mov_b32_e32 v20, v0
	v_mov_b32_e32 v21, v0
	v_mov_b32_e32 v22, v0
	v_mov_b32_e32 v23, v0
	v_mov_b32_e32 v32, v0
	v_mov_b32_e32 v33, v0
	v_mov_b32_e32 v34, v0
	v_mov_b32_e32 v35, v0
	v_mov_b32_e32 v36, v0
	v_mov_b32_e32 v37, v0
	v_mov_b32_e32 v38, v0
	v_mov_b32_e32 v39, v0
	v_mov_b32_e32 v48, v0
	v_mov_b32_e32 v49, v0
	v_mov_b32_e32 v50, v0
	v_mov_b32_e32 v51, v0
	v_mov_b32_e32 v52, v0
	v_mov_b32_e32 v53, v0
	v_mov_b32_e32 v54, v0
	v_mov_b32_e32 v55, v0
	v_mov_b32_e32 v8, v0
	v_mov_b32_e32 v9, v0
	v_mov_b32_e32 v10, v0
	v_mov_b32_e32 v11, v0
	v_mov_b32_e32 v12, v0
	v_mov_b32_e32 v13, v0
	v_mov_b32_e32 v14, v0
	v_mov_b32_e32 v15, v0
	v_mov_b32_e32 v24, v0
	v_mov_b32_e32 v25, v0
	v_mov_b32_e32 v26, v0
	v_mov_b32_e32 v27, v0
	v_mov_b32_e32 v28, v0
	v_mov_b32_e32 v29, v0
	v_mov_b32_e32 v30, v0
	v_mov_b32_e32 v31, v0
	v_mov_b32_e32 v40, v0
	v_mov_b32_e32 v41, v0
	v_mov_b32_e32 v42, v0
	v_mov_b32_e32 v43, v0
	v_mov_b32_e32 v44, v0
	v_mov_b32_e32 v45, v0
	v_mov_b32_e32 v46, v0
	v_mov_b32_e32 v47, v0
	v_mov_b32_e32 v56, v0
	v_mov_b32_e32 v57, v0
	v_mov_b32_e32 v58, v0
	v_mov_b32_e32 v59, v0
	v_mov_b32_e32 v60, v0
	v_mov_b32_e32 v61, v0
	v_mov_b32_e32 v62, v0
	v_mov_b32_e32 v63, v0
	v_mov_b32_e32 v64, v0
	v_mov_b32_e32 v65, v0
	v_mov_b32_e32 v66, v0
	v_mov_b32_e32 v67, v0
	v_mov_b32_e32 v68, v0
	v_mov_b32_e32 v69, v0
	v_mov_b32_e32 v70, v0
	v_mov_b32_e32 v71, v0
	v_mov_b32_e32 v80, v0
	v_mov_b32_e32 v81, v0
	v_mov_b32_e32 v82, v0
	v_mov_b32_e32 v83, v0
	v_mov_b32_e32 v84, v0
	v_mov_b32_e32 v85, v0
	v_mov_b32_e32 v86, v0
	v_mov_b32_e32 v87, v0
	v_mov_b32_e32 v96, v0
	v_mov_b32_e32 v97, v0
	v_mov_b32_e32 v98, v0
	v_mov_b32_e32 v99, v0
	v_mov_b32_e32 v100, v0
	v_mov_b32_e32 v101, v0
	v_mov_b32_e32 v102, v0
	v_mov_b32_e32 v103, v0
	v_mov_b32_e32 v112, v0
	v_mov_b32_e32 v113, v0
	v_mov_b32_e32 v114, v0
	v_mov_b32_e32 v115, v0
	v_mov_b32_e32 v116, v0
	v_mov_b32_e32 v117, v0
	v_mov_b32_e32 v118, v0
	v_mov_b32_e32 v119, v0
	v_mov_b32_e32 v72, v0
	v_mov_b32_e32 v73, v0
	v_mov_b32_e32 v74, v0
	v_mov_b32_e32 v75, v0
	v_mov_b32_e32 v76, v0
	v_mov_b32_e32 v77, v0
	v_mov_b32_e32 v78, v0
	v_mov_b32_e32 v79, v0
	v_mov_b32_e32 v88, v0
	v_mov_b32_e32 v89, v0
	v_mov_b32_e32 v90, v0
	v_mov_b32_e32 v91, v0
	v_mov_b32_e32 v92, v0
	v_mov_b32_e32 v93, v0
	v_mov_b32_e32 v94, v0
	v_mov_b32_e32 v95, v0
	v_mov_b32_e32 v104, v0
	v_mov_b32_e32 v105, v0
	v_mov_b32_e32 v106, v0
	v_mov_b32_e32 v107, v0
	v_mov_b32_e32 v108, v0
	v_mov_b32_e32 v109, v0
	v_mov_b32_e32 v110, v0
	v_mov_b32_e32 v111, v0
	v_mov_b32_e32 v120, v0
	v_mov_b32_e32 v121, v0
	v_mov_b32_e32 v122, v0
	v_mov_b32_e32 v123, v0
	v_mov_b32_e32 v124, v0
	v_mov_b32_e32 v125, v0
	v_mov_b32_e32 v126, v0
	v_mov_b32_e32 v127, v0
	s_mov_b64 s[48:49], 0x80
	v_add_u32_e32 v224, 0x10000, v146
	v_add_u32_e32 v225, 0x14000, v146
	v_add_u32_e32 v226, 0x18000, v146
	v_add_u32_e32 v227, 0x1c000, v146
	s_add_i32 s86, s26, 0x10000
	s_add_i32 s87, s26, 0x14000
	s_add_i32 s88, s26, 0x18000
	s_add_i32 s89, s26, 0x1c000
	ds_read_b128 v[138:141], v224
	ds_read_b128 v[152:155], v224 offset:1024
	ds_read_b128 v[156:159], v224 offset:2048
	ds_read_b128 v[160:163], v224 offset:3072
; #define PG8_STAGE(bufoff, gbase, voff) do { _Pragma("unroll") for (int _i = 0; _i < 2; ++_i) \
;         __builtin_amdgcn_global_load_lds((const unsigned*)((const char*)(gbase) + (voff)[_i]), (LAS unsigned*)(lds + (bufoff) + ldsw + _i * 8192), 16, 0, 0); } while (0)
; #define PG8_LDA(dst, b, h) do { _Pragma("unroll") for (int m = 0; m < 4; ++m) _Pragma("unroll") for (int k = 0; k < 2; ++k) dst[m][k] = *(const LAS bf16x8*)(lds + PG8_SA(b, h) + aoff + m * 2048 + k * 1024); } while (0)
; #define PG8_LDB(dst, b, h) do { _Pragma("unroll") for (int n = 0; n < 2; ++n) _Pragma("unroll") for (int k = 0; k < 2; ++k) dst[n][k] = *(const LAS bf16x8*)(lds + PG8_SB(b, h) + boff + n * 2048 + k * 1024); } while (0)
; #define PG8_MMA(ai, bj, At, Bt) do { __builtin_amdgcn_s_setprio(1); _Pragma("unroll") for (int m = 0; m < 4; ++m) _Pragma("unroll") for (int n = 0; n < 2; ++n) _Pragma("unroll") for (int k = 0; k < 2; ++k) \
;         acc[ai][bj][m][n] = __builtin_amdgcn_mfma_f32_16x16x32_bf16(Bt[n][k], At[m][k], acc[ai][bj][m][n], 0, 0, 0); __builtin_amdgcn_s_setprio(0); } while (0)
; #define PG8_WAIT_V(n) asm volatile("s_waitcnt vmcnt(" #n ")" ::: "memory")
; #define PG8_WAIT_L(n) asm volatile("s_waitcnt lgkmcnt(" #n ")" ::: "memory")
; template <class Epi>
; __device__ __forceinline__ void gemm_phase(LAS unsigned char* lds, const Gemm g, const StaticOrder& S, const Epi& E) {
;     ...
;         for (int t = 0; t < nt; t += 2) {
;             const bool last = (t == nt - 2);
;             const char* a1 = cA + (size_t)(t + 1) * kstep;
;             const char* a2 = last ? nA : cA + (size_t)(t + 2) * kstep; const char* b2 = last ? nB : cB + (size_t)(t + 2) * kstep;
;             const char* a3 = a2 + kstep; const char* b3 = b2 + kstep;
;             PG8_LDB(B0, 0, 0); PG8_SCHED; PG8_LDA(At, 0, 0); PG8_STAGE(PG8_SA(1, 1), a1 + hstep, voffA);
;             PG8_WAIT_L(8); PG8_BAR; PG8_WAIT_L(0); PG8_MMA(0, 0, At, B0); PG8_BAR; PG8_SCHED;
;             PG8_LDB(B1, 0, 1); PG8_STAGE(PG8_SB(0, 0), b2, voffB);
;             PG8_BAR; PG8_WAIT_L(0); PG8_MMA(0, 1, At, B1); PG8_BAR;
;             PG8_LDA(At, 0, 1); PG8_STAGE(PG8_SA(0, 0), a2, voffA);
;             PG8_BAR; PG8_WAIT_L(0); PG8_MMA(1, 0, At, B0); PG8_BAR; PG8_SCHED;
;             PG8_STAGE(PG8_SB(0, 1), b2 + hstep, voffB);
;             PG8_WAIT_V(6); PG8_BAR; PG8_MMA(1, 1, At, B1); PG8_BAR;
.LBB0_165:
	s_add_i32 s44, s18, 2
	s_add_u32 s20, s16, 0x80
	s_addc_u32 s19, s17, 0
	s_cmp_eq_u32 s35, s18
	s_cselect_b32 s18, s10, s20
	s_cselect_b32 s19, s11, s19
	s_cselect_b32 s21, s13, s43
	s_cselect_b32 s20, s12, s42
	s_add_i32 m0, s27, 0xc000
	ds_read_b128 v[164:167], v150
	ds_read_b128 v[168:171], v150 offset:1024
	ds_read_b128 v[172:175], v150 offset:2048
	ds_read_b128 v[176:179], v150 offset:3072
	ds_read_b128 v[180:183], v150 offset:4096
	ds_read_b128 v[184:187], v150 offset:5120
	ds_read_b128 v[188:191], v150 offset:6144
	global_load_lds_dwordx4 v136, s[16:17]
	s_add_i32 m0, s27, 0xe000
	ds_read_b128 v[202:205], v150 offset:7168
	global_load_lds_dwordx4 v134, s[16:17]
	s_waitcnt lgkmcnt(8)
	s_barrier
	s_waitcnt lgkmcnt(0)
	v_mfma_f32_16x16x32_bf16 v[124:127], v[138:141], v[164:167], v[124:127]
	v_mfma_f32_16x16x32_bf16 v[120:123], v[156:159], v[164:167], v[120:123]
	v_mfma_f32_16x16x32_bf16 v[108:111], v[138:141], v[172:175], v[108:111]
	v_mfma_f32_16x16x32_bf16 v[104:107], v[156:159], v[172:175], v[104:107]
	v_mfma_f32_16x16x32_bf16 v[92:95], v[138:141], v[180:183], v[92:95]
	v_mfma_f32_16x16x32_bf16 v[88:91], v[156:159], v[180:183], v[88:91]
	v_mfma_f32_16x16x32_bf16 v[76:79], v[138:141], v[188:191], v[76:79]
	v_mfma_f32_16x16x32_bf16 v[72:75], v[156:159], v[188:191], v[72:75]
	v_mfma_f32_16x16x32_bf16 v[124:127], v[152:155], v[168:171], v[124:127]
	v_mfma_f32_16x16x32_bf16 v[120:123], v[160:163], v[168:171], v[120:123]
	v_mfma_f32_16x16x32_bf16 v[108:111], v[152:155], v[176:179], v[108:111]
	v_mfma_f32_16x16x32_bf16 v[104:107], v[160:163], v[176:179], v[104:107]
	v_mfma_f32_16x16x32_bf16 v[92:95], v[152:155], v[184:187], v[92:95]
	v_mfma_f32_16x16x32_bf16 v[88:91], v[160:163], v[184:187], v[88:91]
	v_mfma_f32_16x16x32_bf16 v[76:79], v[152:155], v[202:205], v[76:79]
	v_mfma_f32_16x16x32_bf16 v[72:75], v[160:163], v[202:205], v[72:75]
	s_barrier
	ds_read_b128 v[206:209], v225
	ds_read_b128 v[210:213], v225 offset:1024
	s_add_u32 s80, s20, 0x80
	s_addc_u32 s81, s21, 0
	s_mov_b32 m0, s86
	ds_read_b128 v[218:221], v225 offset:3072
	global_load_lds_dwordx4 v194, s[20:21]
	s_add_i32 m0, s86, 0x2000
	ds_read_b128 v[214:217], v225 offset:2048
	global_load_lds_dwordx4 v132, s[20:21]
	s_barrier
	s_waitcnt lgkmcnt(0)
	v_mfma_f32_16x16x32_bf16 v[116:119], v[206:209], v[164:167], v[116:119]
	v_mfma_f32_16x16x32_bf16 v[112:115], v[214:217], v[164:167], v[112:115]
	v_mfma_f32_16x16x32_bf16 v[100:103], v[206:209], v[172:175], v[100:103]
	v_mfma_f32_16x16x32_bf16 v[96:99], v[214:217], v[172:175], v[96:99]
	v_mfma_f32_16x16x32_bf16 v[84:87], v[206:209], v[180:183], v[84:87]
	v_mfma_f32_16x16x32_bf16 v[80:83], v[214:217], v[180:183], v[80:83]
	v_mfma_f32_16x16x32_bf16 v[68:71], v[206:209], v[188:191], v[68:71]
	v_mfma_f32_16x16x32_bf16 v[64:67], v[214:217], v[188:191], v[64:67]
	v_mfma_f32_16x16x32_bf16 v[116:119], v[210:213], v[168:171], v[116:119]
	v_mfma_f32_16x16x32_bf16 v[112:115], v[218:221], v[168:171], v[112:115]
	v_mfma_f32_16x16x32_bf16 v[100:103], v[210:213], v[176:179], v[100:103]
	v_mfma_f32_16x16x32_bf16 v[96:99], v[218:221], v[176:179], v[96:99]
	v_mfma_f32_16x16x32_bf16 v[84:87], v[210:213], v[184:187], v[84:87]
	v_mfma_f32_16x16x32_bf16 v[80:83], v[218:221], v[184:187], v[80:83]
	v_mfma_f32_16x16x32_bf16 v[68:71], v[210:213], v[202:205], v[68:71]
	v_mfma_f32_16x16x32_bf16 v[64:67], v[218:221], v[202:205], v[64:67]
	s_mov_b32 m0, s27
	s_add_u32 s82, s18, 0x80
	s_addc_u32 s83, s19, 0
	s_barrier
	ds_read_b128 v[164:167], v150 offset:16384
	ds_read_b128 v[168:171], v150 offset:17408
	ds_read_b128 v[172:175], v150 offset:18432
	ds_read_b128 v[176:179], v150 offset:19456
	ds_read_b128 v[180:183], v150 offset:20480
	ds_read_b128 v[184:187], v150 offset:21504
	ds_read_b128 v[188:191], v150 offset:22528
	global_load_lds_dwordx4 v128, s[18:19]
	s_mov_b32 m0, s28
	ds_read_b128 v[202:205], v150 offset:23552
	global_load_lds_dwordx4 v130, s[18:19]
	s_waitcnt vmcnt(10)
	s_barrier
	s_waitcnt lgkmcnt(0)
	v_mfma_f32_16x16x32_bf16 v[60:63], v[138:141], v[164:167], v[60:63]
	v_mfma_f32_16x16x32_bf16 v[56:59], v[156:159], v[164:167], v[56:59]
	v_mfma_f32_16x16x32_bf16 v[44:47], v[138:141], v[172:175], v[44:47]
	v_mfma_f32_16x16x32_bf16 v[40:43], v[156:159], v[172:175], v[40:43]
	v_mfma_f32_16x16x32_bf16 v[28:31], v[138:141], v[180:183], v[28:31]
	v_mfma_f32_16x16x32_bf16 v[24:27], v[156:159], v[180:183], v[24:27]
	v_mfma_f32_16x16x32_bf16 v[12:15], v[138:141], v[188:191], v[12:15]
	v_mfma_f32_16x16x32_bf16 v[8:11], v[156:159], v[188:191], v[8:11]
	v_mfma_f32_16x16x32_bf16 v[60:63], v[152:155], v[168:171], v[60:63]
	v_mfma_f32_16x16x32_bf16 v[56:59], v[160:163], v[168:171], v[56:59]
	v_mfma_f32_16x16x32_bf16 v[44:47], v[152:155], v[176:179], v[44:47]
	v_mfma_f32_16x16x32_bf16 v[40:43], v[160:163], v[176:179], v[40:43]
	v_mfma_f32_16x16x32_bf16 v[28:31], v[152:155], v[184:187], v[28:31]
	v_mfma_f32_16x16x32_bf16 v[24:27], v[160:163], v[184:187], v[24:27]
	v_mfma_f32_16x16x32_bf16 v[12:15], v[152:155], v[202:205], v[12:15]
	v_mfma_f32_16x16x32_bf16 v[8:11], v[160:163], v[202:205], v[8:11]
	s_barrier
	ds_read_b128 v[138:141], v226
	ds_read_b128 v[152:155], v226 offset:1024
	ds_read_b128 v[156:159], v226 offset:2048
	ds_read_b128 v[160:163], v226 offset:3072
	s_add_u32 s20, s20, s2
	s_addc_u32 s21, s21, s3
	s_add_u32 s84, s20, 0x80
	s_mov_b32 m0, s87
	s_addc_u32 s85, s21, 0
	global_load_lds_dwordx4 v194, s[20:21]
	s_add_i32 m0, s87, 0x2000
	s_nop 0
	global_load_lds_dwordx4 v132, s[20:21]
	s_waitcnt vmcnt(6)
	s_barrier
; #define PG8_STAGE(bufoff, gbase, voff) do { _Pragma("unroll") for (int _i = 0; _i < 2; ++_i) \
;         __builtin_amdgcn_global_load_lds((const unsigned*)((const char*)(gbase) + (voff)[_i]), (LAS unsigned*)(lds + (bufoff) + ldsw + _i * 8192), 16, 0, 0); } while (0)
; #define PG8_LDA(dst, b, h) do { _Pragma("unroll") for (int m = 0; m < 4; ++m) _Pragma("unroll") for (int k = 0; k < 2; ++k) dst[m][k] = *(const LAS bf16x8*)(lds + PG8_SA(b, h) + aoff + m * 2048 + k * 1024); } while (0)
; #define PG8_LDB(dst, b, h) do { _Pragma("unroll") for (int n = 0; n < 2; ++n) _Pragma("unroll") for (int k = 0; k < 2; ++k) dst[n][k] = *(const LAS bf16x8*)(lds + PG8_SB(b, h) + boff + n * 2048 + k * 1024); } while (0)
; #define PG8_MMA(ai, bj, At, Bt) do { __builtin_amdgcn_s_setprio(1); _Pragma("unroll") for (int m = 0; m < 4; ++m) _Pragma("unroll") for (int n = 0; n < 2; ++n) _Pragma("unroll") for (int k = 0; k < 2; ++k) \
;         acc[ai][bj][m][n] = __builtin_amdgcn_mfma_f32_16x16x32_bf16(Bt[n][k], At[m][k], acc[ai][bj][m][n], 0, 0, 0); __builtin_amdgcn_s_setprio(0); } while (0)
; #define PG8_WAIT_V(n) asm volatile("s_waitcnt vmcnt(" #n ")" ::: "memory")
; #define PG8_WAIT_L(n) asm volatile("s_waitcnt lgkmcnt(" #n ")" ::: "memory")
; #define PG8_BAR __builtin_amdgcn_s_barrier()
; #define PG8_SCHED __builtin_amdgcn_sched_barrier(0)
; template <class Epi>
; __device__ __forceinline__ void gemm_phase(LAS unsigned char* lds, const Gemm g, const StaticOrder& S, const Epi& E) {
;     ...
;             PG8_WAIT_V(6); PG8_BAR; PG8_MMA(1, 1, At, B1); PG8_BAR;
;             PG8_LDB(B0, 1, 0); PG8_SCHED; PG8_LDA(At, 1, 0); PG8_STAGE(PG8_SA(0, 1), a2 + hstep, voffA);
;             PG8_WAIT_L(8); PG8_BAR; PG8_WAIT_L(0); PG8_MMA(0, 0, At, B0); PG8_BAR; PG8_SCHED;
;             PG8_LDB(B1, 1, 1); PG8_STAGE(PG8_SB(1, 0), b3, voffB);
;             PG8_BAR; PG8_WAIT_L(0); PG8_MMA(0, 1, At, B1); PG8_BAR;
	v_mfma_f32_16x16x32_bf16 v[52:55], v[206:209], v[164:167], v[52:55]
	v_mfma_f32_16x16x32_bf16 v[48:51], v[214:217], v[164:167], v[48:51]
	v_mfma_f32_16x16x32_bf16 v[36:39], v[206:209], v[172:175], v[36:39]
	v_mfma_f32_16x16x32_bf16 v[32:35], v[214:217], v[172:175], v[32:35]
	v_mfma_f32_16x16x32_bf16 v[20:23], v[206:209], v[180:183], v[20:23]
	v_mfma_f32_16x16x32_bf16 v[16:19], v[214:217], v[180:183], v[16:19]
	v_mfma_f32_16x16x32_bf16 v[4:7], v[206:209], v[188:191], v[4:7]
	v_mfma_f32_16x16x32_bf16 v[0:3], v[214:217], v[188:191], v[0:3]
	v_mfma_f32_16x16x32_bf16 v[52:55], v[210:213], v[168:171], v[52:55]
	v_mfma_f32_16x16x32_bf16 v[48:51], v[218:221], v[168:171], v[48:51]
	v_mfma_f32_16x16x32_bf16 v[36:39], v[210:213], v[176:179], v[36:39]
	v_mfma_f32_16x16x32_bf16 v[32:35], v[218:221], v[176:179], v[32:35]
	v_mfma_f32_16x16x32_bf16 v[20:23], v[210:213], v[184:187], v[20:23]
	v_mfma_f32_16x16x32_bf16 v[16:19], v[218:221], v[184:187], v[16:19]
	v_mfma_f32_16x16x32_bf16 v[4:7], v[210:213], v[202:205], v[4:7]
	v_mfma_f32_16x16x32_bf16 v[0:3], v[218:221], v[202:205], v[0:3]
	s_barrier
	s_add_u32 s18, s18, s2
	s_addc_u32 s19, s19, s3
	s_mov_b32 m0, s29
	ds_read_b128 v[164:167], v150 offset:32768
	ds_read_b128 v[168:171], v150 offset:33792
	ds_read_b128 v[172:175], v150 offset:34816
	ds_read_b128 v[176:179], v150 offset:35840
	ds_read_b128 v[180:183], v150 offset:36864
	ds_read_b128 v[184:187], v150 offset:37888
	ds_read_b128 v[188:191], v150 offset:38912
	global_load_lds_dwordx4 v128, s[18:19]
	s_mov_b32 m0, s30
	ds_read_b128 v[202:205], v150 offset:39936
	global_load_lds_dwordx4 v130, s[18:19]
	s_waitcnt lgkmcnt(8)
	s_barrier
	s_waitcnt lgkmcnt(0)
	v_mfma_f32_16x16x32_bf16 v[124:127], v[138:141], v[164:167], v[124:127]
	v_mfma_f32_16x16x32_bf16 v[120:123], v[156:159], v[164:167], v[120:123]
	v_mfma_f32_16x16x32_bf16 v[108:111], v[138:141], v[172:175], v[108:111]
	v_mfma_f32_16x16x32_bf16 v[104:107], v[156:159], v[172:175], v[104:107]
	v_mfma_f32_16x16x32_bf16 v[92:95], v[138:141], v[180:183], v[92:95]
	v_mfma_f32_16x16x32_bf16 v[88:91], v[156:159], v[180:183], v[88:91]
	v_mfma_f32_16x16x32_bf16 v[76:79], v[138:141], v[188:191], v[76:79]
	v_mfma_f32_16x16x32_bf16 v[72:75], v[156:159], v[188:191], v[72:75]
	v_mfma_f32_16x16x32_bf16 v[124:127], v[152:155], v[168:171], v[124:127]
	v_mfma_f32_16x16x32_bf16 v[120:123], v[160:163], v[168:171], v[120:123]
	v_mfma_f32_16x16x32_bf16 v[108:111], v[152:155], v[176:179], v[108:111]
	v_mfma_f32_16x16x32_bf16 v[104:107], v[160:163], v[176:179], v[104:107]
	v_mfma_f32_16x16x32_bf16 v[92:95], v[152:155], v[184:187], v[92:95]
	v_mfma_f32_16x16x32_bf16 v[88:91], v[160:163], v[184:187], v[88:91]
	v_mfma_f32_16x16x32_bf16 v[76:79], v[152:155], v[202:205], v[76:79]
	v_mfma_f32_16x16x32_bf16 v[72:75], v[160:163], v[202:205], v[72:75]
	s_barrier
	s_mov_b32 m0, s88
	ds_read_b128 v[206:209], v227
	ds_read_b128 v[210:213], v227 offset:1024
	ds_read_b128 v[214:217], v227 offset:2048
	global_load_lds_dwordx4 v194, s[80:81]
	s_add_i32 m0, s88, 0x2000
	ds_read_b128 v[218:221], v227 offset:3072
	global_load_lds_dwordx4 v132, s[80:81]
	s_barrier
	s_waitcnt lgkmcnt(0)
	v_mfma_f32_16x16x32_bf16 v[116:119], v[206:209], v[164:167], v[116:119]
	v_mfma_f32_16x16x32_bf16 v[112:115], v[214:217], v[164:167], v[112:115]
	v_mfma_f32_16x16x32_bf16 v[100:103], v[206:209], v[172:175], v[100:103]
	v_mfma_f32_16x16x32_bf16 v[96:99], v[214:217], v[172:175], v[96:99]
	v_mfma_f32_16x16x32_bf16 v[84:87], v[206:209], v[180:183], v[84:87]
	v_mfma_f32_16x16x32_bf16 v[80:83], v[214:217], v[180:183], v[80:83]
	v_mfma_f32_16x16x32_bf16 v[68:71], v[206:209], v[188:191], v[68:71]
	v_mfma_f32_16x16x32_bf16 v[64:67], v[214:217], v[188:191], v[64:67]
	v_mfma_f32_16x16x32_bf16 v[116:119], v[210:213], v[168:171], v[116:119]
	v_mfma_f32_16x16x32_bf16 v[112:115], v[218:221], v[168:171], v[112:115]
	v_mfma_f32_16x16x32_bf16 v[100:103], v[210:213], v[176:179], v[100:103]
	v_mfma_f32_16x16x32_bf16 v[96:99], v[218:221], v[176:179], v[96:99]
	v_mfma_f32_16x16x32_bf16 v[84:87], v[210:213], v[184:187], v[84:87]
	v_mfma_f32_16x16x32_bf16 v[80:83], v[218:221], v[184:187], v[80:83]
	v_mfma_f32_16x16x32_bf16 v[68:71], v[210:213], v[202:205], v[68:71]
	v_mfma_f32_16x16x32_bf16 v[64:67], v[218:221], v[202:205], v[64:67]
	s_mov_b32 m0, s31
	s_barrier
; #define PG8_STAGE(bufoff, gbase, voff) do { _Pragma("unroll") for (int _i = 0; _i < 2; ++_i) \
;         __builtin_amdgcn_global_load_lds((const unsigned*)((const char*)(gbase) + (voff)[_i]), (LAS unsigned*)(lds + (bufoff) + ldsw + _i * 8192), 16, 0, 0); } while (0)
; #define PG8_LDA(dst, b, h) do { _Pragma("unroll") for (int m = 0; m < 4; ++m) _Pragma("unroll") for (int k = 0; k < 2; ++k) dst[m][k] = *(const LAS bf16x8*)(lds + PG8_SA(b, h) + aoff + m * 2048 + k * 1024); } while (0)
; #define PG8_MMA(ai, bj, At, Bt) do { __builtin_amdgcn_s_setprio(1); _Pragma("unroll") for (int m = 0; m < 4; ++m) _Pragma("unroll") for (int n = 0; n < 2; ++n) _Pragma("unroll") for (int k = 0; k < 2; ++k) \
;         acc[ai][bj][m][n] = __builtin_amdgcn_mfma_f32_16x16x32_bf16(Bt[n][k], At[m][k], acc[ai][bj][m][n], 0, 0, 0); __builtin_amdgcn_s_setprio(0); } while (0)
; #define PG8_WAIT_V(n) asm volatile("s_waitcnt vmcnt(" #n ")" ::: "memory")
; #define PG8_WAIT_L(n) asm volatile("s_waitcnt lgkmcnt(" #n ")" ::: "memory")
; #define PG8_BAR __builtin_amdgcn_s_barrier()
; #define PG8_SCHED __builtin_amdgcn_sched_barrier(0)
; template <class Epi>
; __device__ __forceinline__ void gemm_phase(LAS unsigned char* lds, const Gemm g, const StaticOrder& S, const Epi& E) {
;     ...
;             PG8_BAR; PG8_WAIT_L(0); PG8_MMA(0, 1, At, B1); PG8_BAR;
;             PG8_LDA(At, 1, 1); PG8_STAGE(PG8_SA(1, 0), a3, voffA);
;             PG8_BAR; PG8_WAIT_L(0); PG8_MMA(1, 0, At, B0); PG8_BAR; PG8_SCHED;
;             PG8_STAGE(PG8_SB(1, 1), b3 + hstep, voffB);
;             PG8_WAIT_V(6); PG8_BAR; PG8_MMA(1, 1, At, B1); PG8_BAR;
;         }
	ds_read_b128 v[164:167], v150 offset:49152
	ds_read_b128 v[168:171], v150 offset:50176
	ds_read_b128 v[172:175], v150 offset:51200
	ds_read_b128 v[176:179], v150 offset:52224
	ds_read_b128 v[180:183], v150 offset:53248
	ds_read_b128 v[184:187], v150 offset:54272
	ds_read_b128 v[188:191], v150 offset:55296
	global_load_lds_dwordx4 v128, s[82:83]
	s_mov_b32 m0, s33
	ds_read_b128 v[202:205], v150 offset:56320
	global_load_lds_dwordx4 v130, s[82:83]
	s_waitcnt vmcnt(10)
	s_barrier
	s_waitcnt lgkmcnt(0)
	v_mfma_f32_16x16x32_bf16 v[60:63], v[138:141], v[164:167], v[60:63]
	v_mfma_f32_16x16x32_bf16 v[56:59], v[156:159], v[164:167], v[56:59]
	v_mfma_f32_16x16x32_bf16 v[44:47], v[138:141], v[172:175], v[44:47]
	v_mfma_f32_16x16x32_bf16 v[40:43], v[156:159], v[172:175], v[40:43]
	v_mfma_f32_16x16x32_bf16 v[28:31], v[138:141], v[180:183], v[28:31]
	v_mfma_f32_16x16x32_bf16 v[24:27], v[156:159], v[180:183], v[24:27]
	v_mfma_f32_16x16x32_bf16 v[12:15], v[138:141], v[188:191], v[12:15]
	v_mfma_f32_16x16x32_bf16 v[8:11], v[156:159], v[188:191], v[8:11]
	v_mfma_f32_16x16x32_bf16 v[60:63], v[152:155], v[168:171], v[60:63]
	v_mfma_f32_16x16x32_bf16 v[56:59], v[160:163], v[168:171], v[56:59]
	v_mfma_f32_16x16x32_bf16 v[44:47], v[152:155], v[176:179], v[44:47]
	v_mfma_f32_16x16x32_bf16 v[40:43], v[160:163], v[176:179], v[40:43]
	v_mfma_f32_16x16x32_bf16 v[28:31], v[152:155], v[184:187], v[28:31]
	v_mfma_f32_16x16x32_bf16 v[24:27], v[160:163], v[184:187], v[24:27]
	v_mfma_f32_16x16x32_bf16 v[12:15], v[152:155], v[202:205], v[12:15]
	v_mfma_f32_16x16x32_bf16 v[8:11], v[160:163], v[202:205], v[8:11]
	s_barrier
	ds_read_b128 v[138:141], v224
	ds_read_b128 v[152:155], v224 offset:1024
	ds_read_b128 v[156:159], v224 offset:2048
	ds_read_b128 v[160:163], v224 offset:3072
	s_mov_b32 m0, s89
	s_nop 0
	global_load_lds_dwordx4 v194, s[84:85]
	s_add_i32 m0, s89, 0x2000
	s_nop 0
	global_load_lds_dwordx4 v132, s[84:85]
	s_waitcnt vmcnt(6)
	s_barrier
	v_mfma_f32_16x16x32_bf16 v[52:55], v[206:209], v[164:167], v[52:55]
	v_mfma_f32_16x16x32_bf16 v[48:51], v[214:217], v[164:167], v[48:51]
	v_mfma_f32_16x16x32_bf16 v[36:39], v[206:209], v[172:175], v[36:39]
	v_mfma_f32_16x16x32_bf16 v[32:35], v[214:217], v[172:175], v[32:35]
	v_mfma_f32_16x16x32_bf16 v[20:23], v[206:209], v[180:183], v[20:23]
	v_mfma_f32_16x16x32_bf16 v[16:19], v[214:217], v[180:183], v[16:19]
	v_mfma_f32_16x16x32_bf16 v[4:7], v[206:209], v[188:191], v[4:7]
	v_mfma_f32_16x16x32_bf16 v[0:3], v[214:217], v[188:191], v[0:3]
	v_mfma_f32_16x16x32_bf16 v[52:55], v[210:213], v[168:171], v[52:55]
	v_mfma_f32_16x16x32_bf16 v[48:51], v[218:221], v[168:171], v[48:51]
	v_mfma_f32_16x16x32_bf16 v[36:39], v[210:213], v[176:179], v[36:39]
	v_mfma_f32_16x16x32_bf16 v[32:35], v[218:221], v[176:179], v[32:35]
	v_mfma_f32_16x16x32_bf16 v[20:23], v[210:213], v[184:187], v[20:23]
	v_mfma_f32_16x16x32_bf16 v[16:19], v[218:221], v[184:187], v[16:19]
	v_mfma_f32_16x16x32_bf16 v[4:7], v[210:213], v[202:205], v[4:7]
	v_mfma_f32_16x16x32_bf16 v[0:3], v[218:221], v[202:205], v[0:3]
	s_add_u32 s42, s42, 0x100
	s_addc_u32 s43, s43, 0
	s_add_u32 s16, s16, 0x100
	s_addc_u32 s17, s17, 0
	s_cmp_ge_i32 s44, s34
	s_mov_b32 s18, s44
	s_barrier
	s_cbranch_scc0 .LBB0_165
	s_waitcnt lgkmcnt(0)

; #define PG8_STAGE(bufoff, gbase, voff) do { _Pragma("unroll") for (int _i = 0; _i < 2; ++_i) \
;         __builtin_amdgcn_global_load_lds((const unsigned*)((const char*)(gbase) + (voff)[_i]), (LAS unsigned*)(lds + (bufoff) + ldsw + _i * 8192), 16, 0, 0); } while (0)
; #define PG8_LDA(dst, b, h) do { _Pragma("unroll") for (int m = 0; m < 4; ++m) _Pragma("unroll") for (int k = 0; k < 2; ++k) dst[m][k] = *(const LAS bf16x8*)(lds + PG8_SA(b, h) + aoff + m * 2048 + k * 1024); } while (0)
; #define PG8_WAIT_V(n) asm volatile("s_waitcnt vmcnt(" #n ")" ::: "memory")
; #define PG8_BAR __builtin_amdgcn_s_barrier()
; template <class Epi>
; __device__ __forceinline__ void gemm_phase(LAS unsigned char* lds, const Gemm g, const StaticOrder& S, const Epi& E) {
;     ...
;     f32x4 acc[2][2][4][2];
; #pragma unroll
;     for (int a = 0; a < 2; ++a)
; #pragma unroll
;         for (int b = 0; b < 2; ++b)
; #pragma unroll
;             for (int m = 0; m < 4; ++m)
; #pragma unroll
;                 for (int n = 0; n < 2; ++n) acc[a][b][m][n] = (f32x4){0.f, 0.f, 0.f, 0.f};
;     bf16x8 At[4][2], B0[2][2], B1[2][2];
;     const char* cA = (const char*)g.A + (size_t)cur.pm * tstep; const char* cB = (const char*)g.Bt + (size_t)cur.pn * tstep;
;     if (Epi::PRE) E.stash(E.prefetch(cur.pm, tid), lds, 0, tid);
;     PG8_STAGE(PG8_SB(0, 0), cB, voffB); PG8_STAGE(PG8_SA(0, 0), cA, voffA); PG8_STAGE(PG8_SB(0, 1), cB + hstep, voffB); PG8_STAGE(PG8_SA(0, 1), cA + hstep, voffA);
;     if (wr == 1) PG8_BAR;
;     PG8_WAIT_V(4); PG8_BAR;
;     PG8_STAGE(PG8_SB(1, 0), cB + kstep, voffB); PG8_STAGE(PG8_SA(1, 0), cA + kstep, voffA); PG8_STAGE(PG8_SB(1, 1), cB + hstep + kstep, voffB);
;     PG8_WAIT_V(6); PG8_BAR;
;     for (;;) {
;         const bool has_next = S.next(ui + 1, nxt);
;         const char* nA = has_next ? (const char*)g.A + (size_t)nxt.pm * tstep : cA; const char* nB = has_next ? (const char*)g.Bt + (size_t)nxt.pn * tstep : cB;
;         for (int t = 0; t < nt; t += 2) {
;             const bool last = (t == nt - 2);
;             const char* a1 = cA + (size_t)(t + 1) * kstep;
;             const char* a2 = last ? nA : cA + (size_t)(t + 2) * kstep; const char* b2 = last ? nB : cB + (size_t)(t + 2) * kstep;
;             const char* a3 = a2 + kstep; const char* b3 = b2 + kstep;
;             PG8_LDB(B0, 0, 0); PG8_SCHED; PG8_LDA(At, 0, 0); PG8_STAGE(PG8_SA(1, 1), a1 + hstep, voffA);
.LBB0_526:
	v_mov_b32_e32 v127, 0
	s_andn2_b64 vcc, exec, s[6:7]
	v_mov_b32_e32 v126, v127
	v_mov_b32_e32 v125, v127
	v_mov_b32_e32 v124, v127
	v_mov_b32_e32 v123, v127
	v_mov_b32_e32 v122, v127
	v_mov_b32_e32 v121, v127
	v_mov_b32_e32 v120, v127
	v_mov_b32_e32 v111, v127
	v_mov_b32_e32 v110, v127
	v_mov_b32_e32 v109, v127
	v_mov_b32_e32 v108, v127
	v_mov_b32_e32 v107, v127
	v_mov_b32_e32 v106, v127
	v_mov_b32_e32 v105, v127
	v_mov_b32_e32 v104, v127
	v_mov_b32_e32 v95, v127
	v_mov_b32_e32 v94, v127
	v_mov_b32_e32 v93, v127
	v_mov_b32_e32 v92, v127
	v_mov_b32_e32 v91, v127
	v_mov_b32_e32 v90, v127
	v_mov_b32_e32 v89, v127
	v_mov_b32_e32 v88, v127
	v_mov_b32_e32 v79, v127
	v_mov_b32_e32 v78, v127
	v_mov_b32_e32 v77, v127
	v_mov_b32_e32 v76, v127
	v_mov_b32_e32 v75, v127
	v_mov_b32_e32 v74, v127
	v_mov_b32_e32 v73, v127
	v_mov_b32_e32 v72, v127
	v_mov_b32_e32 v119, v127
	v_mov_b32_e32 v118, v127
	v_mov_b32_e32 v117, v127
	v_mov_b32_e32 v116, v127
	v_mov_b32_e32 v115, v127
	v_mov_b32_e32 v114, v127
	v_mov_b32_e32 v113, v127
	v_mov_b32_e32 v112, v127
	v_mov_b32_e32 v103, v127
	v_mov_b32_e32 v102, v127
	v_mov_b32_e32 v101, v127
	v_mov_b32_e32 v100, v127
	v_mov_b32_e32 v99, v127
	v_mov_b32_e32 v98, v127
	v_mov_b32_e32 v97, v127
	v_mov_b32_e32 v96, v127
	v_mov_b32_e32 v87, v127
	v_mov_b32_e32 v86, v127
	v_mov_b32_e32 v85, v127
	v_mov_b32_e32 v84, v127
	v_mov_b32_e32 v83, v127
	v_mov_b32_e32 v82, v127
	v_mov_b32_e32 v81, v127
	v_mov_b32_e32 v80, v127
	v_mov_b32_e32 v71, v127
	v_mov_b32_e32 v70, v127
	v_mov_b32_e32 v69, v127
	v_mov_b32_e32 v68, v127
	v_mov_b32_e32 v67, v127
	v_mov_b32_e32 v66, v127
	v_mov_b32_e32 v65, v127
	v_mov_b32_e32 v64, v127
	v_mov_b32_e32 v63, v127
	v_mov_b32_e32 v62, v127
	v_mov_b32_e32 v61, v127
	v_mov_b32_e32 v60, v127
	v_mov_b32_e32 v59, v127
	v_mov_b32_e32 v58, v127
	v_mov_b32_e32 v57, v127
	v_mov_b32_e32 v56, v127
	v_mov_b32_e32 v47, v127
	v_mov_b32_e32 v46, v127
	v_mov_b32_e32 v45, v127
	v_mov_b32_e32 v44, v127
	v_mov_b32_e32 v43, v127
	v_mov_b32_e32 v42, v127
	v_mov_b32_e32 v41, v127
	v_mov_b32_e32 v40, v127
	v_mov_b32_e32 v31, v127
	v_mov_b32_e32 v30, v127
	v_mov_b32_e32 v29, v127
	v_mov_b32_e32 v28, v127
	v_mov_b32_e32 v27, v127
	v_mov_b32_e32 v26, v127
	v_mov_b32_e32 v25, v127
	v_mov_b32_e32 v24, v127
	v_mov_b32_e32 v15, v127
	v_mov_b32_e32 v14, v127
	v_mov_b32_e32 v13, v127
	v_mov_b32_e32 v12, v127
	v_mov_b32_e32 v11, v127
	v_mov_b32_e32 v10, v127
	v_mov_b32_e32 v9, v127
	v_mov_b32_e32 v8, v127
	v_mov_b32_e32 v55, v127
	v_mov_b32_e32 v54, v127
	v_mov_b32_e32 v53, v127
	v_mov_b32_e32 v52, v127
	v_mov_b32_e32 v51, v127
	v_mov_b32_e32 v50, v127
	v_mov_b32_e32 v49, v127
	v_mov_b32_e32 v48, v127
	v_mov_b32_e32 v39, v127
	v_mov_b32_e32 v38, v127
	v_mov_b32_e32 v37, v127
	v_mov_b32_e32 v36, v127
	v_mov_b32_e32 v35, v127
	v_mov_b32_e32 v34, v127
	v_mov_b32_e32 v33, v127
	v_mov_b32_e32 v32, v127
	v_mov_b32_e32 v23, v127
	v_mov_b32_e32 v22, v127
	v_mov_b32_e32 v21, v127
	v_mov_b32_e32 v20, v127
	v_mov_b32_e32 v19, v127
	v_mov_b32_e32 v18, v127
	v_mov_b32_e32 v17, v127
	v_mov_b32_e32 v16, v127
	v_mov_b32_e32 v7, v127
	v_mov_b32_e32 v6, v127
	v_mov_b32_e32 v5, v127
	v_mov_b32_e32 v4, v127
	v_mov_b32_e32 v3, v127
	v_mov_b32_e32 v2, v127
	v_mov_b32_e32 v1, v127
	v_mov_b32_e32 v0, v127
	s_cbranch_vccnz .LBB0_529
	s_add_u32 s40, s18, 0x100
	s_addc_u32 s41, s19, 0
	s_add_u32 s16, s16, 0x80
	v_mov_b32_e32 v0, 0
	s_addc_u32 s17, s17, 0
	s_mov_b32 s18, 0
	v_mov_b32_e32 v1, v0
	v_mov_b32_e32 v2, v0
	v_mov_b32_e32 v3, v0
	v_mov_b32_e32 v4, v0
	v_mov_b32_e32 v5, v0
	v_mov_b32_e32 v6, v0
	v_mov_b32_e32 v7, v0
	v_mov_b32_e32 v16, v0
	v_mov_b32_e32 v17, v0
	v_mov_b32_e32 v18, v0
	v_mov_b32_e32 v19, v0
	v_mov_b32_e32 v20, v0
	v_mov_b32_e32 v21, v0
	v_mov_b32_e32 v22, v0
	v_mov_b32_e32 v23, v0
	v_mov_b32_e32 v32, v0
	v_mov_b32_e32 v33, v0
	v_mov_b32_e32 v34, v0
	v_mov_b32_e32 v35, v0
	v_mov_b32_e32 v36, v0
	v_mov_b32_e32 v37, v0
	v_mov_b32_e32 v38, v0
	v_mov_b32_e32 v39, v0
	v_mov_b32_e32 v48, v0
	v_mov_b32_e32 v49, v0
	v_mov_b32_e32 v50, v0
	v_mov_b32_e32 v51, v0
	v_mov_b32_e32 v52, v0
	v_mov_b32_e32 v53, v0
	v_mov_b32_e32 v54, v0
	v_mov_b32_e32 v55, v0
	v_mov_b32_e32 v8, v0
	v_mov_b32_e32 v9, v0
	v_mov_b32_e32 v10, v0
	v_mov_b32_e32 v11, v0
	v_mov_b32_e32 v12, v0
	v_mov_b32_e32 v13, v0
	v_mov_b32_e32 v14, v0
	v_mov_b32_e32 v15, v0
	v_mov_b32_e32 v24, v0
	v_mov_b32_e32 v25, v0
	v_mov_b32_e32 v26, v0
	v_mov_b32_e32 v27, v0
	v_mov_b32_e32 v28, v0
	v_mov_b32_e32 v29, v0
	v_mov_b32_e32 v30, v0
	v_mov_b32_e32 v31, v0
	v_mov_b32_e32 v40, v0
	v_mov_b32_e32 v41, v0
	v_mov_b32_e32 v42, v0
	v_mov_b32_e32 v43, v0
	v_mov_b32_e32 v44, v0
	v_mov_b32_e32 v45, v0
	v_mov_b32_e32 v46, v0
	v_mov_b32_e32 v47, v0
	v_mov_b32_e32 v56, v0
	v_mov_b32_e32 v57, v0
	v_mov_b32_e32 v58, v0
	v_mov_b32_e32 v59, v0
	v_mov_b32_e32 v60, v0
	v_mov_b32_e32 v61, v0
	v_mov_b32_e32 v62, v0
	v_mov_b32_e32 v63, v0
	v_mov_b32_e32 v64, v0
	v_mov_b32_e32 v65, v0
	v_mov_b32_e32 v66, v0
	v_mov_b32_e32 v67, v0
	v_mov_b32_e32 v68, v0
	v_mov_b32_e32 v69, v0
	v_mov_b32_e32 v70, v0
	v_mov_b32_e32 v71, v0
	v_mov_b32_e32 v80, v0
	v_mov_b32_e32 v81, v0
	v_mov_b32_e32 v82, v0
	v_mov_b32_e32 v83, v0
	v_mov_b32_e32 v84, v0
	v_mov_b32_e32 v85, v0
	v_mov_b32_e32 v86, v0
	v_mov_b32_e32 v87, v0
	v_mov_b32_e32 v96, v0
	v_mov_b32_e32 v97, v0
	v_mov_b32_e32 v98, v0
	v_mov_b32_e32 v99, v0
	v_mov_b32_e32 v100, v0
	v_mov_b32_e32 v101, v0
	v_mov_b32_e32 v102, v0
	v_mov_b32_e32 v103, v0
	v_mov_b32_e32 v112, v0
	v_mov_b32_e32 v113, v0
	v_mov_b32_e32 v114, v0
	v_mov_b32_e32 v115, v0
	v_mov_b32_e32 v116, v0
	v_mov_b32_e32 v117, v0
	v_mov_b32_e32 v118, v0
	v_mov_b32_e32 v119, v0
	v_mov_b32_e32 v72, v0
	v_mov_b32_e32 v73, v0
	v_mov_b32_e32 v74, v0
	v_mov_b32_e32 v75, v0
	v_mov_b32_e32 v76, v0
	v_mov_b32_e32 v77, v0
	v_mov_b32_e32 v78, v0
	v_mov_b32_e32 v79, v0
	v_mov_b32_e32 v88, v0
	v_mov_b32_e32 v89, v0
	v_mov_b32_e32 v90, v0
	v_mov_b32_e32 v91, v0
	v_mov_b32_e32 v92, v0
	v_mov_b32_e32 v93, v0
	v_mov_b32_e32 v94, v0
	v_mov_b32_e32 v95, v0
	v_mov_b32_e32 v104, v0
	v_mov_b32_e32 v105, v0
	v_mov_b32_e32 v106, v0
	v_mov_b32_e32 v107, v0
	v_mov_b32_e32 v108, v0
	v_mov_b32_e32 v109, v0
	v_mov_b32_e32 v110, v0
	v_mov_b32_e32 v111, v0
	v_mov_b32_e32 v120, v0
	v_mov_b32_e32 v121, v0
	v_mov_b32_e32 v122, v0
	v_mov_b32_e32 v123, v0
	v_mov_b32_e32 v124, v0
	v_mov_b32_e32 v125, v0
	v_mov_b32_e32 v126, v0
	v_mov_b32_e32 v127, v0
	s_mov_b64 s[46:47], 0x80
	v_add_u32_e32 v224, 0x10000, v144
	v_add_u32_e32 v225, 0x14000, v144
	v_add_u32_e32 v226, 0x18000, v144
	v_add_u32_e32 v227, 0x1c000, v144
	s_add_i32 s86, s24, 0x10000
	s_add_i32 s87, s24, 0x14000
	s_add_i32 s88, s24, 0x18000
	s_add_i32 s89, s24, 0x1c000
	ds_read_b128 v[138:141], v224
	ds_read_b128 v[150:153], v224 offset:1024
	ds_read_b128 v[154:157], v224 offset:2048
	ds_read_b128 v[158:161], v224 offset:3072
; #define PG8_STAGE(bufoff, gbase, voff) do { _Pragma("unroll") for (int _i = 0; _i < 2; ++_i) \
;         __builtin_amdgcn_global_load_lds((const unsigned*)((const char*)(gbase) + (voff)[_i]), (LAS unsigned*)(lds + (bufoff) + ldsw + _i * 8192), 16, 0, 0); } while (0)
; #define PG8_LDA(dst, b, h) do { _Pragma("unroll") for (int m = 0; m < 4; ++m) _Pragma("unroll") for (int k = 0; k < 2; ++k) dst[m][k] = *(const LAS bf16x8*)(lds + PG8_SA(b, h) + aoff + m * 2048 + k * 1024); } while (0)
; #define PG8_LDB(dst, b, h) do { _Pragma("unroll") for (int n = 0; n < 2; ++n) _Pragma("unroll") for (int k = 0; k < 2; ++k) dst[n][k] = *(const LAS bf16x8*)(lds + PG8_SB(b, h) + boff + n * 2048 + k * 1024); } while (0)
; #define PG8_MMA(ai, bj, At, Bt) do { __builtin_amdgcn_s_setprio(1); _Pragma("unroll") for (int m = 0; m < 4; ++m) _Pragma("unroll") for (int n = 0; n < 2; ++n) _Pragma("unroll") for (int k = 0; k < 2; ++k) \
;         acc[ai][bj][m][n] = __builtin_amdgcn_mfma_f32_16x16x32_bf16(Bt[n][k], At[m][k], acc[ai][bj][m][n], 0, 0, 0); __builtin_amdgcn_s_setprio(0); } while (0)
; #define PG8_WAIT_V(n) asm volatile("s_waitcnt vmcnt(" #n ")" ::: "memory")
; #define PG8_WAIT_L(n) asm volatile("s_waitcnt lgkmcnt(" #n ")" ::: "memory")
; template <class Epi>
; __device__ __forceinline__ void gemm_phase(LAS unsigned char* lds, const Gemm g, const StaticOrder& S, const Epi& E) {
;     ...
;         for (int t = 0; t < nt; t += 2) {
;             const bool last = (t == nt - 2);
;             const char* a1 = cA + (size_t)(t + 1) * kstep;
;             const char* a2 = last ? nA : cA + (size_t)(t + 2) * kstep; const char* b2 = last ? nB : cB + (size_t)(t + 2) * kstep;
;             const char* a3 = a2 + kstep; const char* b3 = b2 + kstep;
;             PG8_LDB(B0, 0, 0); PG8_SCHED; PG8_LDA(At, 0, 0); PG8_STAGE(PG8_SA(1, 1), a1 + hstep, voffA);
;             PG8_WAIT_L(8); PG8_BAR; PG8_WAIT_L(0); PG8_MMA(0, 0, At, B0); PG8_BAR; PG8_SCHED;
;             PG8_LDB(B1, 0, 1); PG8_STAGE(PG8_SB(0, 0), b2, voffB);
;             PG8_BAR; PG8_WAIT_L(0); PG8_MMA(0, 1, At, B1); PG8_BAR;
;             PG8_LDA(At, 0, 1); PG8_STAGE(PG8_SA(0, 0), a2, voffA);
;             PG8_BAR; PG8_WAIT_L(0); PG8_MMA(1, 0, At, B0); PG8_BAR; PG8_SCHED;
;             PG8_STAGE(PG8_SB(0, 1), b2 + hstep, voffB);
;             PG8_WAIT_V(6); PG8_BAR; PG8_MMA(1, 1, At, B1); PG8_BAR;
.LBB0_528:
	s_add_i32 s42, s18, 2
	s_add_u32 s20, s16, 0x80
	s_addc_u32 s19, s17, 0
	s_cmp_eq_u32 s33, s18
	s_cselect_b32 s18, s10, s20
	s_cselect_b32 s19, s11, s19
	s_cselect_b32 s21, s13, s41
	s_cselect_b32 s20, s12, s40
	s_add_i32 m0, s25, 0xc000
	ds_read_b128 v[162:165], v148
	ds_read_b128 v[166:169], v148 offset:1024
	ds_read_b128 v[170:173], v148 offset:2048
	ds_read_b128 v[174:177], v148 offset:3072
	ds_read_b128 v[178:181], v148 offset:4096
	ds_read_b128 v[182:185], v148 offset:5120
	ds_read_b128 v[186:189], v148 offset:6144
	global_load_lds_dwordx4 v136, s[16:17]
	s_add_i32 m0, s25, 0xe000
	ds_read_b128 v[202:205], v148 offset:7168
	global_load_lds_dwordx4 v134, s[16:17]
	s_waitcnt lgkmcnt(8)
	s_barrier
	s_waitcnt lgkmcnt(0)
	v_mfma_f32_16x16x32_bf16 v[124:127], v[138:141], v[162:165], v[124:127]
	v_mfma_f32_16x16x32_bf16 v[120:123], v[154:157], v[162:165], v[120:123]
	v_mfma_f32_16x16x32_bf16 v[108:111], v[138:141], v[170:173], v[108:111]
	v_mfma_f32_16x16x32_bf16 v[104:107], v[154:157], v[170:173], v[104:107]
	v_mfma_f32_16x16x32_bf16 v[92:95], v[138:141], v[178:181], v[92:95]
	v_mfma_f32_16x16x32_bf16 v[88:91], v[154:157], v[178:181], v[88:91]
	v_mfma_f32_16x16x32_bf16 v[76:79], v[138:141], v[186:189], v[76:79]
	v_mfma_f32_16x16x32_bf16 v[72:75], v[154:157], v[186:189], v[72:75]
	v_mfma_f32_16x16x32_bf16 v[124:127], v[150:153], v[166:169], v[124:127]
	v_mfma_f32_16x16x32_bf16 v[120:123], v[158:161], v[166:169], v[120:123]
	v_mfma_f32_16x16x32_bf16 v[108:111], v[150:153], v[174:177], v[108:111]
	v_mfma_f32_16x16x32_bf16 v[104:107], v[158:161], v[174:177], v[104:107]
	v_mfma_f32_16x16x32_bf16 v[92:95], v[150:153], v[182:185], v[92:95]
	v_mfma_f32_16x16x32_bf16 v[88:91], v[158:161], v[182:185], v[88:91]
	v_mfma_f32_16x16x32_bf16 v[76:79], v[150:153], v[202:205], v[76:79]
	v_mfma_f32_16x16x32_bf16 v[72:75], v[158:161], v[202:205], v[72:75]
	s_barrier
	s_add_u32 s80, s20, 0x80
	s_addc_u32 s81, s21, 0
	s_mov_b32 m0, s86
	ds_read_b128 v[206:209], v225
	ds_read_b128 v[210:213], v225 offset:1024
	ds_read_b128 v[214:217], v225 offset:2048
	global_load_lds_dwordx4 v194, s[20:21]
	s_add_i32 m0, s86, 0x2000
	ds_read_b128 v[218:221], v225 offset:3072
	global_load_lds_dwordx4 v132, s[20:21]
	s_barrier
	s_waitcnt lgkmcnt(0)
	v_mfma_f32_16x16x32_bf16 v[116:119], v[206:209], v[162:165], v[116:119]
	v_mfma_f32_16x16x32_bf16 v[112:115], v[214:217], v[162:165], v[112:115]
	v_mfma_f32_16x16x32_bf16 v[100:103], v[206:209], v[170:173], v[100:103]
	v_mfma_f32_16x16x32_bf16 v[96:99], v[214:217], v[170:173], v[96:99]
	v_mfma_f32_16x16x32_bf16 v[84:87], v[206:209], v[178:181], v[84:87]
	v_mfma_f32_16x16x32_bf16 v[80:83], v[214:217], v[178:181], v[80:83]
	v_mfma_f32_16x16x32_bf16 v[68:71], v[206:209], v[186:189], v[68:71]
	v_mfma_f32_16x16x32_bf16 v[64:67], v[214:217], v[186:189], v[64:67]
	v_mfma_f32_16x16x32_bf16 v[116:119], v[210:213], v[166:169], v[116:119]
	v_mfma_f32_16x16x32_bf16 v[112:115], v[218:221], v[166:169], v[112:115]
	v_mfma_f32_16x16x32_bf16 v[100:103], v[210:213], v[174:177], v[100:103]
	v_mfma_f32_16x16x32_bf16 v[96:99], v[218:221], v[174:177], v[96:99]
	v_mfma_f32_16x16x32_bf16 v[84:87], v[210:213], v[182:185], v[84:87]
	v_mfma_f32_16x16x32_bf16 v[80:83], v[218:221], v[182:185], v[80:83]
	v_mfma_f32_16x16x32_bf16 v[68:71], v[210:213], v[202:205], v[68:71]
	v_mfma_f32_16x16x32_bf16 v[64:67], v[218:221], v[202:205], v[64:67]
	s_mov_b32 m0, s25
	s_add_u32 s82, s18, 0x80
	s_addc_u32 s83, s19, 0
	s_barrier
	ds_read_b128 v[162:165], v148 offset:16384
	ds_read_b128 v[166:169], v148 offset:17408
	ds_read_b128 v[170:173], v148 offset:18432
	ds_read_b128 v[174:177], v148 offset:19456
	ds_read_b128 v[178:181], v148 offset:20480
	ds_read_b128 v[182:185], v148 offset:21504
	ds_read_b128 v[186:189], v148 offset:22528
	global_load_lds_dwordx4 v128, s[18:19]
	s_mov_b32 m0, s26
	ds_read_b128 v[202:205], v148 offset:23552
	global_load_lds_dwordx4 v130, s[18:19]
	s_waitcnt vmcnt(10)
	s_barrier
	s_waitcnt lgkmcnt(0)
	v_mfma_f32_16x16x32_bf16 v[60:63], v[138:141], v[162:165], v[60:63]
	v_mfma_f32_16x16x32_bf16 v[56:59], v[154:157], v[162:165], v[56:59]
	v_mfma_f32_16x16x32_bf16 v[44:47], v[138:141], v[170:173], v[44:47]
	v_mfma_f32_16x16x32_bf16 v[40:43], v[154:157], v[170:173], v[40:43]
	v_mfma_f32_16x16x32_bf16 v[28:31], v[138:141], v[178:181], v[28:31]
	v_mfma_f32_16x16x32_bf16 v[24:27], v[154:157], v[178:181], v[24:27]
	v_mfma_f32_16x16x32_bf16 v[12:15], v[138:141], v[186:189], v[12:15]
	v_mfma_f32_16x16x32_bf16 v[8:11], v[154:157], v[186:189], v[8:11]
	v_mfma_f32_16x16x32_bf16 v[60:63], v[150:153], v[166:169], v[60:63]
	v_mfma_f32_16x16x32_bf16 v[56:59], v[158:161], v[166:169], v[56:59]
	v_mfma_f32_16x16x32_bf16 v[44:47], v[150:153], v[174:177], v[44:47]
	v_mfma_f32_16x16x32_bf16 v[40:43], v[158:161], v[174:177], v[40:43]
	v_mfma_f32_16x16x32_bf16 v[28:31], v[150:153], v[182:185], v[28:31]
	v_mfma_f32_16x16x32_bf16 v[24:27], v[158:161], v[182:185], v[24:27]
	v_mfma_f32_16x16x32_bf16 v[12:15], v[150:153], v[202:205], v[12:15]
	v_mfma_f32_16x16x32_bf16 v[8:11], v[158:161], v[202:205], v[8:11]
	s_barrier
	ds_read_b128 v[138:141], v226
	ds_read_b128 v[150:153], v226 offset:1024
	ds_read_b128 v[154:157], v226 offset:2048
	ds_read_b128 v[158:161], v226 offset:3072
	s_add_u32 s20, s20, s2
	s_addc_u32 s21, s21, s3
	s_add_u32 s84, s20, 0x80
	s_mov_b32 m0, s87
	s_addc_u32 s85, s21, 0
	global_load_lds_dwordx4 v194, s[20:21]
	s_add_i32 m0, s87, 0x2000
	s_nop 0
	global_load_lds_dwordx4 v132, s[20:21]
	s_waitcnt vmcnt(6)
	s_barrier
; #define PG8_STAGE(bufoff, gbase, voff) do { _Pragma("unroll") for (int _i = 0; _i < 2; ++_i) \
;         __builtin_amdgcn_global_load_lds((const unsigned*)((const char*)(gbase) + (voff)[_i]), (LAS unsigned*)(lds + (bufoff) + ldsw + _i * 8192), 16, 0, 0); } while (0)
; #define PG8_LDA(dst, b, h) do { _Pragma("unroll") for (int m = 0; m < 4; ++m) _Pragma("unroll") for (int k = 0; k < 2; ++k) dst[m][k] = *(const LAS bf16x8*)(lds + PG8_SA(b, h) + aoff + m * 2048 + k * 1024); } while (0)
; #define PG8_LDB(dst, b, h) do { _Pragma("unroll") for (int n = 0; n < 2; ++n) _Pragma("unroll") for (int k = 0; k < 2; ++k) dst[n][k] = *(const LAS bf16x8*)(lds + PG8_SB(b, h) + boff + n * 2048 + k * 1024); } while (0)
; #define PG8_MMA(ai, bj, At, Bt) do { __builtin_amdgcn_s_setprio(1); _Pragma("unroll") for (int m = 0; m < 4; ++m) _Pragma("unroll") for (int n = 0; n < 2; ++n) _Pragma("unroll") for (int k = 0; k < 2; ++k) \
;         acc[ai][bj][m][n] = __builtin_amdgcn_mfma_f32_16x16x32_bf16(Bt[n][k], At[m][k], acc[ai][bj][m][n], 0, 0, 0); __builtin_amdgcn_s_setprio(0); } while (0)
; #define PG8_WAIT_V(n) asm volatile("s_waitcnt vmcnt(" #n ")" ::: "memory")
; #define PG8_WAIT_L(n) asm volatile("s_waitcnt lgkmcnt(" #n ")" ::: "memory")
; #define PG8_BAR __builtin_amdgcn_s_barrier()
; #define PG8_SCHED __builtin_amdgcn_sched_barrier(0)
; template <class Epi>
; __device__ __forceinline__ void gemm_phase(LAS unsigned char* lds, const Gemm g, const StaticOrder& S, const Epi& E) {
;     ...
;             PG8_WAIT_V(6); PG8_BAR; PG8_MMA(1, 1, At, B1); PG8_BAR;
;             PG8_LDB(B0, 1, 0); PG8_SCHED; PG8_LDA(At, 1, 0); PG8_STAGE(PG8_SA(0, 1), a2 + hstep, voffA);
;             PG8_WAIT_L(8); PG8_BAR; PG8_WAIT_L(0); PG8_MMA(0, 0, At, B0); PG8_BAR; PG8_SCHED;
;             PG8_LDB(B1, 1, 1); PG8_STAGE(PG8_SB(1, 0), b3, voffB);
;             PG8_BAR; PG8_WAIT_L(0); PG8_MMA(0, 1, At, B1); PG8_BAR;
	v_mfma_f32_16x16x32_bf16 v[52:55], v[206:209], v[162:165], v[52:55]
	v_mfma_f32_16x16x32_bf16 v[48:51], v[214:217], v[162:165], v[48:51]
	v_mfma_f32_16x16x32_bf16 v[36:39], v[206:209], v[170:173], v[36:39]
	v_mfma_f32_16x16x32_bf16 v[32:35], v[214:217], v[170:173], v[32:35]
	v_mfma_f32_16x16x32_bf16 v[20:23], v[206:209], v[178:181], v[20:23]
	v_mfma_f32_16x16x32_bf16 v[16:19], v[214:217], v[178:181], v[16:19]
	v_mfma_f32_16x16x32_bf16 v[4:7], v[206:209], v[186:189], v[4:7]
	v_mfma_f32_16x16x32_bf16 v[0:3], v[214:217], v[186:189], v[0:3]
	v_mfma_f32_16x16x32_bf16 v[52:55], v[210:213], v[166:169], v[52:55]
	v_mfma_f32_16x16x32_bf16 v[48:51], v[218:221], v[166:169], v[48:51]
	v_mfma_f32_16x16x32_bf16 v[36:39], v[210:213], v[174:177], v[36:39]
	v_mfma_f32_16x16x32_bf16 v[32:35], v[218:221], v[174:177], v[32:35]
	v_mfma_f32_16x16x32_bf16 v[20:23], v[210:213], v[182:185], v[20:23]
	v_mfma_f32_16x16x32_bf16 v[16:19], v[218:221], v[182:185], v[16:19]
	v_mfma_f32_16x16x32_bf16 v[4:7], v[210:213], v[202:205], v[4:7]
	v_mfma_f32_16x16x32_bf16 v[0:3], v[218:221], v[202:205], v[0:3]
	s_barrier
	s_add_u32 s18, s18, s2
	s_addc_u32 s19, s19, s3
	s_mov_b32 m0, s27
	ds_read_b128 v[162:165], v148 offset:32768
	ds_read_b128 v[166:169], v148 offset:33792
	ds_read_b128 v[170:173], v148 offset:34816
	ds_read_b128 v[174:177], v148 offset:35840
	ds_read_b128 v[178:181], v148 offset:36864
	ds_read_b128 v[182:185], v148 offset:37888
	ds_read_b128 v[186:189], v148 offset:38912
	global_load_lds_dwordx4 v128, s[18:19]
	s_mov_b32 m0, s28
	ds_read_b128 v[202:205], v148 offset:39936
	global_load_lds_dwordx4 v130, s[18:19]
	s_waitcnt lgkmcnt(8)
	s_barrier
	s_waitcnt lgkmcnt(0)
	v_mfma_f32_16x16x32_bf16 v[124:127], v[138:141], v[162:165], v[124:127]
	v_mfma_f32_16x16x32_bf16 v[120:123], v[154:157], v[162:165], v[120:123]
	v_mfma_f32_16x16x32_bf16 v[108:111], v[138:141], v[170:173], v[108:111]
	v_mfma_f32_16x16x32_bf16 v[104:107], v[154:157], v[170:173], v[104:107]
	v_mfma_f32_16x16x32_bf16 v[92:95], v[138:141], v[178:181], v[92:95]
	v_mfma_f32_16x16x32_bf16 v[88:91], v[154:157], v[178:181], v[88:91]
	v_mfma_f32_16x16x32_bf16 v[76:79], v[138:141], v[186:189], v[76:79]
	v_mfma_f32_16x16x32_bf16 v[72:75], v[154:157], v[186:189], v[72:75]
	v_mfma_f32_16x16x32_bf16 v[124:127], v[150:153], v[166:169], v[124:127]
	v_mfma_f32_16x16x32_bf16 v[120:123], v[158:161], v[166:169], v[120:123]
	v_mfma_f32_16x16x32_bf16 v[108:111], v[150:153], v[174:177], v[108:111]
	v_mfma_f32_16x16x32_bf16 v[104:107], v[158:161], v[174:177], v[104:107]
	v_mfma_f32_16x16x32_bf16 v[92:95], v[150:153], v[182:185], v[92:95]
	v_mfma_f32_16x16x32_bf16 v[88:91], v[158:161], v[182:185], v[88:91]
	v_mfma_f32_16x16x32_bf16 v[76:79], v[150:153], v[202:205], v[76:79]
	v_mfma_f32_16x16x32_bf16 v[72:75], v[158:161], v[202:205], v[72:75]
	s_barrier
	s_mov_b32 m0, s88
	ds_read_b128 v[206:209], v227
	ds_read_b128 v[210:213], v227 offset:1024
	ds_read_b128 v[214:217], v227 offset:2048
	global_load_lds_dwordx4 v194, s[80:81]
	s_add_i32 m0, s88, 0x2000
	ds_read_b128 v[218:221], v227 offset:3072
	global_load_lds_dwordx4 v132, s[80:81]
	s_barrier
	s_waitcnt lgkmcnt(0)
	v_mfma_f32_16x16x32_bf16 v[116:119], v[206:209], v[162:165], v[116:119]
	v_mfma_f32_16x16x32_bf16 v[112:115], v[214:217], v[162:165], v[112:115]
	v_mfma_f32_16x16x32_bf16 v[100:103], v[206:209], v[170:173], v[100:103]
	v_mfma_f32_16x16x32_bf16 v[96:99], v[214:217], v[170:173], v[96:99]
	v_mfma_f32_16x16x32_bf16 v[84:87], v[206:209], v[178:181], v[84:87]
	v_mfma_f32_16x16x32_bf16 v[80:83], v[214:217], v[178:181], v[80:83]
	v_mfma_f32_16x16x32_bf16 v[68:71], v[206:209], v[186:189], v[68:71]
	v_mfma_f32_16x16x32_bf16 v[64:67], v[214:217], v[186:189], v[64:67]
	v_mfma_f32_16x16x32_bf16 v[116:119], v[210:213], v[166:169], v[116:119]
	v_mfma_f32_16x16x32_bf16 v[112:115], v[218:221], v[166:169], v[112:115]
	v_mfma_f32_16x16x32_bf16 v[100:103], v[210:213], v[174:177], v[100:103]
	v_mfma_f32_16x16x32_bf16 v[96:99], v[218:221], v[174:177], v[96:99]
	v_mfma_f32_16x16x32_bf16 v[84:87], v[210:213], v[182:185], v[84:87]
	v_mfma_f32_16x16x32_bf16 v[80:83], v[218:221], v[182:185], v[80:83]
	v_mfma_f32_16x16x32_bf16 v[68:71], v[210:213], v[202:205], v[68:71]
	v_mfma_f32_16x16x32_bf16 v[64:67], v[218:221], v[202:205], v[64:67]
	s_mov_b32 m0, s29
	s_barrier
; #define PG8_STAGE(bufoff, gbase, voff) do { _Pragma("unroll") for (int _i = 0; _i < 2; ++_i) \
;         __builtin_amdgcn_global_load_lds((const unsigned*)((const char*)(gbase) + (voff)[_i]), (LAS unsigned*)(lds + (bufoff) + ldsw + _i * 8192), 16, 0, 0); } while (0)
; #define PG8_LDA(dst, b, h) do { _Pragma("unroll") for (int m = 0; m < 4; ++m) _Pragma("unroll") for (int k = 0; k < 2; ++k) dst[m][k] = *(const LAS bf16x8*)(lds + PG8_SA(b, h) + aoff + m * 2048 + k * 1024); } while (0)
; #define PG8_MMA(ai, bj, At, Bt) do { __builtin_amdgcn_s_setprio(1); _Pragma("unroll") for (int m = 0; m < 4; ++m) _Pragma("unroll") for (int n = 0; n < 2; ++n) _Pragma("unroll") for (int k = 0; k < 2; ++k) \
;         acc[ai][bj][m][n] = __builtin_amdgcn_mfma_f32_16x16x32_bf16(Bt[n][k], At[m][k], acc[ai][bj][m][n], 0, 0, 0); __builtin_amdgcn_s_setprio(0); } while (0)
; #define PG8_WAIT_V(n) asm volatile("s_waitcnt vmcnt(" #n ")" ::: "memory")
; #define PG8_WAIT_L(n) asm volatile("s_waitcnt lgkmcnt(" #n ")" ::: "memory")
; #define PG8_BAR __builtin_amdgcn_s_barrier()
; #define PG8_SCHED __builtin_amdgcn_sched_barrier(0)
; template <class Epi>
; __device__ __forceinline__ void gemm_phase(LAS unsigned char* lds, const Gemm g, const StaticOrder& S, const Epi& E) {
;     ...
;             PG8_BAR; PG8_WAIT_L(0); PG8_MMA(0, 1, At, B1); PG8_BAR;
;             PG8_LDA(At, 1, 1); PG8_STAGE(PG8_SA(1, 0), a3, voffA);
;             PG8_BAR; PG8_WAIT_L(0); PG8_MMA(1, 0, At, B0); PG8_BAR; PG8_SCHED;
;             PG8_STAGE(PG8_SB(1, 1), b3 + hstep, voffB);
;             PG8_WAIT_V(6); PG8_BAR; PG8_MMA(1, 1, At, B1); PG8_BAR;
;         }
	ds_read_b128 v[162:165], v148 offset:49152
	ds_read_b128 v[166:169], v148 offset:50176
	ds_read_b128 v[170:173], v148 offset:51200
	ds_read_b128 v[174:177], v148 offset:52224
	ds_read_b128 v[178:181], v148 offset:53248
	ds_read_b128 v[182:185], v148 offset:54272
	ds_read_b128 v[186:189], v148 offset:55296
	global_load_lds_dwordx4 v128, s[82:83]
	s_mov_b32 m0, s30
	ds_read_b128 v[202:205], v148 offset:56320
	global_load_lds_dwordx4 v130, s[82:83]
	s_waitcnt vmcnt(10)
	s_barrier
	s_waitcnt lgkmcnt(0)
	v_mfma_f32_16x16x32_bf16 v[60:63], v[138:141], v[162:165], v[60:63]
	v_mfma_f32_16x16x32_bf16 v[56:59], v[154:157], v[162:165], v[56:59]
	v_mfma_f32_16x16x32_bf16 v[44:47], v[138:141], v[170:173], v[44:47]
	v_mfma_f32_16x16x32_bf16 v[40:43], v[154:157], v[170:173], v[40:43]
	v_mfma_f32_16x16x32_bf16 v[28:31], v[138:141], v[178:181], v[28:31]
	v_mfma_f32_16x16x32_bf16 v[24:27], v[154:157], v[178:181], v[24:27]
	v_mfma_f32_16x16x32_bf16 v[12:15], v[138:141], v[186:189], v[12:15]
	v_mfma_f32_16x16x32_bf16 v[8:11], v[154:157], v[186:189], v[8:11]
	v_mfma_f32_16x16x32_bf16 v[60:63], v[150:153], v[166:169], v[60:63]
	v_mfma_f32_16x16x32_bf16 v[56:59], v[158:161], v[166:169], v[56:59]
	v_mfma_f32_16x16x32_bf16 v[44:47], v[150:153], v[174:177], v[44:47]
	v_mfma_f32_16x16x32_bf16 v[40:43], v[158:161], v[174:177], v[40:43]
	v_mfma_f32_16x16x32_bf16 v[28:31], v[150:153], v[182:185], v[28:31]
	v_mfma_f32_16x16x32_bf16 v[24:27], v[158:161], v[182:185], v[24:27]
	v_mfma_f32_16x16x32_bf16 v[12:15], v[150:153], v[202:205], v[12:15]
	v_mfma_f32_16x16x32_bf16 v[8:11], v[158:161], v[202:205], v[8:11]
	s_barrier
	ds_read_b128 v[138:141], v224
	ds_read_b128 v[150:153], v224 offset:1024
	ds_read_b128 v[154:157], v224 offset:2048
	ds_read_b128 v[158:161], v224 offset:3072
	s_mov_b32 m0, s89
	s_nop 0
	global_load_lds_dwordx4 v194, s[84:85]
	s_add_i32 m0, s89, 0x2000
	s_nop 0
	global_load_lds_dwordx4 v132, s[84:85]
	s_waitcnt vmcnt(6)
	s_barrier
	v_mfma_f32_16x16x32_bf16 v[52:55], v[206:209], v[162:165], v[52:55]
	v_mfma_f32_16x16x32_bf16 v[48:51], v[214:217], v[162:165], v[48:51]
	v_mfma_f32_16x16x32_bf16 v[36:39], v[206:209], v[170:173], v[36:39]
	v_mfma_f32_16x16x32_bf16 v[32:35], v[214:217], v[170:173], v[32:35]
	v_mfma_f32_16x16x32_bf16 v[20:23], v[206:209], v[178:181], v[20:23]
	v_mfma_f32_16x16x32_bf16 v[16:19], v[214:217], v[178:181], v[16:19]
	v_mfma_f32_16x16x32_bf16 v[4:7], v[206:209], v[186:189], v[4:7]
	v_mfma_f32_16x16x32_bf16 v[0:3], v[214:217], v[186:189], v[0:3]
	v_mfma_f32_16x16x32_bf16 v[52:55], v[210:213], v[166:169], v[52:55]
	v_mfma_f32_16x16x32_bf16 v[48:51], v[218:221], v[166:169], v[48:51]
	v_mfma_f32_16x16x32_bf16 v[36:39], v[210:213], v[174:177], v[36:39]
	v_mfma_f32_16x16x32_bf16 v[32:35], v[218:221], v[174:177], v[32:35]
	v_mfma_f32_16x16x32_bf16 v[20:23], v[210:213], v[182:185], v[20:23]
	v_mfma_f32_16x16x32_bf16 v[16:19], v[218:221], v[182:185], v[16:19]
	v_mfma_f32_16x16x32_bf16 v[4:7], v[210:213], v[202:205], v[4:7]
	v_mfma_f32_16x16x32_bf16 v[0:3], v[218:221], v[202:205], v[0:3]
	s_add_u32 s40, s40, 0x100
	s_addc_u32 s41, s41, 0
	s_add_u32 s16, s16, 0x100
	s_addc_u32 s17, s17, 0
	s_cmp_ge_i32 s42, s31
	s_mov_b32 s18, s42
	s_barrier
	s_cbranch_scc0 .LBB0_528
	s_waitcnt lgkmcnt(0)
